# FFN GEMM loops: MFMA issue order changed so src0 fragment stays constant over 4 consecutive MFMAs (operand toggling / power experiment)
# baseline (speedup 1.0000x reference)
;     __device__ __forceinline__ size_t a_koff(int t) const { return (size_t)t * 128; }
;     __device__ __forceinline__ size_t a_koff(int t) const { return (size_t)t * 32768; }
; #define PG8_STAGE(bufoff, gbase, voff) do { _Pragma("unroll") for (int _i = 0; _i < 2; ++_i) \
;         __builtin_amdgcn_global_load_lds((const unsigned*)((const char*)(gbase) + (size_t)_i * p##voff + (voff)), (LAS unsigned*)(lds + (bufoff) + ldsw + _i * 8192), 16, 0, 0); } while (0)
; #define PG8_LDA(dst, b, h) do { _Pragma("unroll") for (int m = 0; m < 4; ++m) _Pragma("unroll") for (int k = 0; k < 2; ++k) dst[m][k] = *(const LAS bf16x8*)(lds + PG8_SA(b, h) + aoff + m * 2048 + k * 1024); } while (0)
; #define PG8_LDB(dst, b, h) do { _Pragma("unroll") for (int n = 0; n < 2; ++n) _Pragma("unroll") for (int k = 0; k < 2; ++k) dst[n][k] = *(const LAS bf16x8*)(lds + PG8_SB(b, h) + boff + n * 2048 + k * 1024); } while (0)
; #define PG8_WAIT_V(n) asm volatile("s_waitcnt vmcnt(" #n ")" ::: "memory")
; #define PG8_WAIT_L(n) asm volatile("s_waitcnt lgkmcnt(" #n ")" ::: "memory")
; #define PG8_BAR __builtin_amdgcn_s_barrier()
; #define PG8_SCHED __builtin_amdgcn_sched_barrier(0)
;     __device__ __forceinline__ size_t a_koff(int t) const { return ((size_t)(t >> 1) * 3072 + (size_t)(t & 1) * 64) * 2; }
;     __device__ __forceinline__ size_t a_koff(int t) const { return (size_t)t * 128; }
;     ...
;         for (int t = 0; t < nt; t += 2) {
;             const bool last = (t == nt - 2);
;             const char* a1 = cA + g.a_koff(t + 1);
;             const char* a2 = last ? nA : cA + g.a_koff(t + 2); const char* b2 = last ? nB : cB + (size_t)(t + 2) * kstep;
;             const char* a3 = last ? nA + g.a_koff(1) : cA + g.a_koff(t + 3); const char* b3 = b2 + kstep;
;             PG8_LDB(B0, 0, 0); PG8_LDB(B1, 0, 1); PG8_SCHED; PG8_LDA(At, 0, 0); PG8_STAGE(PG8_SA(1, 1), a1 + hstepA, voffA);
;             PG8_WAIT_V(8); PG8_WAIT_L(0); PG8_BAR; PG8_MMA(0, 0, At, B0); PG8_MMA(0, 1, At, B1); PG8_BAR; PG8_SCHED;
;             PG8_LDA(At, 0, 1); PG8_STAGE(PG8_SB(0, 0), b2, voffB); PG8_STAGE(PG8_SB(0, 1), b2 + hstepB, voffB); PG8_STAGE(PG8_SA(0, 0), a2, voffA);
;             PG8_WAIT_V(8); PG8_WAIT_L(0); PG8_BAR; PG8_MMA(1, 0, At, B0); PG8_MMA(1, 1, At, B1); PG8_BAR; PG8_SCHED;
.LBB0_1206:
	ds_read_b128 v[148:151], v144
	ds_read_b128 v[152:155], v144 offset:1024
	ds_read_b128 v[156:159], v144 offset:2048
	ds_read_b128 v[160:163], v144 offset:3072
	ds_read_b128 v[164:167], v145
	ds_read_b128 v[168:171], v145 offset:1024
	ds_read_b128 v[172:175], v145 offset:2048
	ds_read_b128 v[176:179], v145 offset:3072
	s_add_u32 s46, s42, s44
	s_addc_u32 s47, s43, s45
	s_add_u32 s74, s46, 0x10000
	s_addc_u32 s75, s47, 0
	s_add_u32 s46, s46, 0x18000
	s_addc_u32 s47, s47, 0
	s_cmp_eq_u32 s44, 0x1f0000
	s_cselect_b32 s47, s68, s47
	s_cselect_b32 s46, s67, s46
	s_cselect_b32 s73, s29, s70
	s_cselect_b32 s72, s66, s69
	s_cselect_b32 s75, s35, s75
	s_cselect_b32 s74, s65, s74
	v_lshl_add_u64 v[184:185], v[142:143], 0, s[44:45]
	v_lshl_add_u64 v[216:217], v[184:185], 0, s[76:77]
	s_add_i32 m0, s52, 0xc000
	ds_read_b128 v[180:183], v146
	ds_read_b128 v[188:191], v146 offset:1024
	ds_read_b128 v[192:195], v146 offset:2048
	ds_read_b128 v[196:199], v146 offset:3072
	ds_read_b128 v[200:203], v146 offset:4096
	ds_read_b128 v[204:207], v146 offset:5120
	ds_read_b128 v[208:211], v146 offset:6144
	ds_read_b128 v[212:215], v146 offset:7168
	global_load_lds_dwordx4 v[216:217], off
	v_lshl_add_u64 v[184:185], v[184:185], 0, s[26:27]
	s_add_i32 m0, s52, 0xe000
	s_nop 0
	global_load_lds_dwordx4 v[184:185], off
	s_waitcnt vmcnt(8)
	s_waitcnt lgkmcnt(0)
	s_barrier
	s_setprio 1
	s_waitcnt lgkmcnt(0)
	v_mfma_f32_16x16x32_bf16 v[126:129], v[148:151], v[180:183], v[126:129]
	v_mfma_f32_16x16x32_bf16 v[110:113], v[148:151], v[192:195], v[110:113]
	v_mfma_f32_16x16x32_bf16 v[94:97], v[148:151], v[200:203], v[94:97]
	v_mfma_f32_16x16x32_bf16 v[78:81], v[148:151], v[208:211], v[78:81]
	v_mfma_f32_16x16x32_bf16 v[122:125], v[156:159], v[180:183], v[122:125]
	v_mfma_f32_16x16x32_bf16 v[106:109], v[156:159], v[192:195], v[106:109]
	v_mfma_f32_16x16x32_bf16 v[90:93], v[156:159], v[200:203], v[90:93]
	v_mfma_f32_16x16x32_bf16 v[74:77], v[156:159], v[208:211], v[74:77]
	v_mfma_f32_16x16x32_bf16 v[126:129], v[152:155], v[188:191], v[126:129]
	v_mfma_f32_16x16x32_bf16 v[110:113], v[152:155], v[196:199], v[110:113]
	v_mfma_f32_16x16x32_bf16 v[94:97], v[152:155], v[204:207], v[94:97]
	v_mfma_f32_16x16x32_bf16 v[78:81], v[152:155], v[212:215], v[78:81]
	v_mfma_f32_16x16x32_bf16 v[122:125], v[160:163], v[188:191], v[122:125]
	v_mfma_f32_16x16x32_bf16 v[106:109], v[160:163], v[196:199], v[106:109]
	v_mfma_f32_16x16x32_bf16 v[90:93], v[160:163], v[204:207], v[90:93]
	v_mfma_f32_16x16x32_bf16 v[74:77], v[160:163], v[212:215], v[74:77]
	s_setprio 0
	s_setprio 1
	v_mfma_f32_16x16x32_bf16 v[118:121], v[164:167], v[180:183], v[118:121]
	v_mfma_f32_16x16x32_bf16 v[102:105], v[164:167], v[192:195], v[102:105]
	v_mfma_f32_16x16x32_bf16 v[86:89], v[164:167], v[200:203], v[86:89]
	v_mfma_f32_16x16x32_bf16 v[70:73], v[164:167], v[208:211], v[70:73]
	v_mfma_f32_16x16x32_bf16 v[114:117], v[172:175], v[180:183], v[114:117]
	v_mfma_f32_16x16x32_bf16 v[98:101], v[172:175], v[192:195], v[98:101]
	v_mfma_f32_16x16x32_bf16 v[82:85], v[172:175], v[200:203], v[82:85]
	v_mfma_f32_16x16x32_bf16 v[66:69], v[172:175], v[208:211], v[66:69]
	v_mfma_f32_16x16x32_bf16 v[118:121], v[168:171], v[188:191], v[118:121]
	v_mfma_f32_16x16x32_bf16 v[102:105], v[168:171], v[196:199], v[102:105]
	v_mfma_f32_16x16x32_bf16 v[86:89], v[168:171], v[204:207], v[86:89]
	v_mfma_f32_16x16x32_bf16 v[70:73], v[168:171], v[212:215], v[70:73]
	v_mfma_f32_16x16x32_bf16 v[114:117], v[176:179], v[188:191], v[114:117]
	v_mfma_f32_16x16x32_bf16 v[98:101], v[176:179], v[196:199], v[98:101]
	v_mfma_f32_16x16x32_bf16 v[82:85], v[176:179], v[204:207], v[82:85]
	v_mfma_f32_16x16x32_bf16 v[66:69], v[176:179], v[212:215], v[66:69]
	s_setprio 0
	s_barrier
	v_lshl_add_u64 v[184:185], s[72:73], 0, v[132:133]
	s_add_i32 s72, s63, s50
	s_mov_b32 m0, s72
	ds_read_b128 v[180:183], v146 offset:16384
	ds_read_b128 v[188:191], v146 offset:17408
	ds_read_b128 v[192:195], v146 offset:18432
	ds_read_b128 v[196:199], v146 offset:19456
	ds_read_b128 v[200:203], v146 offset:20480
	ds_read_b128 v[204:207], v146 offset:21504
	ds_read_b128 v[208:211], v146 offset:22528
	ds_read_b128 v[212:215], v146 offset:23552
	global_load_lds_dwordx4 v[184:185], off
	v_lshl_add_u64 v[216:217], v[184:185], 0, s[4:5]
	s_add_i32 m0, s72, 0x2000
	s_add_i32 s72, s64, s50
	global_load_lds_dwordx4 v[216:217], off
	v_lshl_add_u64 v[216:217], v[184:185], 0, s[6:7]
	s_mov_b32 m0, s72
	s_nop 0
	global_load_lds_dwordx4 v[216:217], off
	v_lshl_add_u64 v[216:217], v[184:185], 0, s[8:9]
	s_add_i32 m0, s72, 0x2000
	s_nop 0
	global_load_lds_dwordx4 v[216:217], off
	v_lshl_add_u64 v[216:217], s[74:75], 0, v[130:131]
	s_mov_b32 m0, s52
	v_lshl_add_u64 v[218:219], v[216:217], 0, s[10:11]
	global_load_lds_dwordx4 v[216:217], off
	s_mov_b32 m0, s53
	s_nop 0
	global_load_lds_dwordx4 v[218:219], off
	s_waitcnt vmcnt(8)
	s_waitcnt lgkmcnt(0)
	s_barrier
; #define PG8_STAGE(bufoff, gbase, voff) do { _Pragma("unroll") for (int _i = 0; _i < 2; ++_i) \
;         __builtin_amdgcn_global_load_lds((const unsigned*)((const char*)(gbase) + (size_t)_i * p##voff + (voff)), (LAS unsigned*)(lds + (bufoff) + ldsw + _i * 8192), 16, 0, 0); } while (0)
; #define PG8_LDA(dst, b, h) do { _Pragma("unroll") for (int m = 0; m < 4; ++m) _Pragma("unroll") for (int k = 0; k < 2; ++k) dst[m][k] = *(const LAS bf16x8*)(lds + PG8_SA(b, h) + aoff + m * 2048 + k * 1024); } while (0)
; #define PG8_LDB(dst, b, h) do { _Pragma("unroll") for (int n = 0; n < 2; ++n) _Pragma("unroll") for (int k = 0; k < 2; ++k) dst[n][k] = *(const LAS bf16x8*)(lds + PG8_SB(b, h) + boff + n * 2048 + k * 1024); } while (0)
; #define PG8_WAIT_V(n) asm volatile("s_waitcnt vmcnt(" #n ")" ::: "memory")
; #define PG8_WAIT_L(n) asm volatile("s_waitcnt lgkmcnt(" #n ")" ::: "memory")
; #define PG8_BAR __builtin_amdgcn_s_barrier()
; #define PG8_SCHED __builtin_amdgcn_sched_barrier(0)
;     ...
;             PG8_LDA(At, 0, 1); PG8_STAGE(PG8_SB(0, 0), b2, voffB); PG8_STAGE(PG8_SB(0, 1), b2 + hstepB, voffB); PG8_STAGE(PG8_SA(0, 0), a2, voffA);
;             PG8_WAIT_V(8); PG8_WAIT_L(0); PG8_BAR; PG8_MMA(1, 0, At, B0); PG8_MMA(1, 1, At, B1); PG8_BAR; PG8_SCHED;
;             PG8_LDB(B0, 1, 0); PG8_LDB(B1, 1, 1); PG8_SCHED; PG8_LDA(At, 1, 0); PG8_STAGE(PG8_SA(0, 1), a2 + hstepA, voffA);
;             PG8_WAIT_V(8); PG8_WAIT_L(0); PG8_BAR; PG8_MMA(0, 0, At, B0); PG8_MMA(0, 1, At, B1); PG8_BAR; PG8_SCHED;
;             PG8_LDA(At, 1, 1); PG8_STAGE(PG8_SB(1, 0), b3, voffB); PG8_STAGE(PG8_SB(1, 1), b3 + hstepB, voffB); PG8_STAGE(PG8_SA(1, 0), a3, voffA);
	s_setprio 1
	s_waitcnt lgkmcnt(0)
	v_mfma_f32_16x16x32_bf16 v[62:65], v[148:151], v[180:183], v[62:65]
	v_mfma_f32_16x16x32_bf16 v[46:49], v[148:151], v[192:195], v[46:49]
	v_mfma_f32_16x16x32_bf16 v[30:33], v[148:151], v[200:203], v[30:33]
	v_mfma_f32_16x16x32_bf16 v[14:17], v[148:151], v[208:211], v[14:17]
	v_mfma_f32_16x16x32_bf16 v[58:61], v[156:159], v[180:183], v[58:61]
	v_mfma_f32_16x16x32_bf16 v[42:45], v[156:159], v[192:195], v[42:45]
	v_mfma_f32_16x16x32_bf16 v[26:29], v[156:159], v[200:203], v[26:29]
	v_mfma_f32_16x16x32_bf16 v[10:13], v[156:159], v[208:211], v[10:13]
	v_mfma_f32_16x16x32_bf16 v[62:65], v[152:155], v[188:191], v[62:65]
	v_mfma_f32_16x16x32_bf16 v[46:49], v[152:155], v[196:199], v[46:49]
	v_mfma_f32_16x16x32_bf16 v[30:33], v[152:155], v[204:207], v[30:33]
	v_mfma_f32_16x16x32_bf16 v[14:17], v[152:155], v[212:215], v[14:17]
	v_mfma_f32_16x16x32_bf16 v[58:61], v[160:163], v[188:191], v[58:61]
	v_mfma_f32_16x16x32_bf16 v[42:45], v[160:163], v[196:199], v[42:45]
	v_mfma_f32_16x16x32_bf16 v[26:29], v[160:163], v[204:207], v[26:29]
	v_mfma_f32_16x16x32_bf16 v[10:13], v[160:163], v[212:215], v[10:13]
	s_setprio 0
	s_setprio 1
	v_mfma_f32_16x16x32_bf16 v[54:57], v[164:167], v[180:183], v[54:57]
	v_mfma_f32_16x16x32_bf16 v[38:41], v[164:167], v[192:195], v[38:41]
	v_mfma_f32_16x16x32_bf16 v[22:25], v[164:167], v[200:203], v[22:25]
	v_mfma_f32_16x16x32_bf16 v[6:9], v[164:167], v[208:211], v[6:9]
	v_mfma_f32_16x16x32_bf16 v[50:53], v[172:175], v[180:183], v[50:53]
	v_mfma_f32_16x16x32_bf16 v[34:37], v[172:175], v[192:195], v[34:37]
	v_mfma_f32_16x16x32_bf16 v[18:21], v[172:175], v[200:203], v[18:21]
	v_mfma_f32_16x16x32_bf16 v[2:5], v[172:175], v[208:211], v[2:5]
	v_mfma_f32_16x16x32_bf16 v[54:57], v[168:171], v[188:191], v[54:57]
	v_mfma_f32_16x16x32_bf16 v[38:41], v[168:171], v[196:199], v[38:41]
	v_mfma_f32_16x16x32_bf16 v[22:25], v[168:171], v[204:207], v[22:25]
	v_mfma_f32_16x16x32_bf16 v[6:9], v[168:171], v[212:215], v[6:9]
	v_mfma_f32_16x16x32_bf16 v[50:53], v[176:179], v[188:191], v[50:53]
	v_mfma_f32_16x16x32_bf16 v[34:37], v[176:179], v[196:199], v[34:37]
	v_mfma_f32_16x16x32_bf16 v[18:21], v[176:179], v[204:207], v[18:21]
	v_mfma_f32_16x16x32_bf16 v[2:5], v[176:179], v[212:215], v[2:5]
	s_setprio 0
	s_barrier
	s_add_i32 s72, 0, 0x18000
	s_add_i32 s73, 0, 0x1c000
	v_add_u32_e32 v160, s72, v1
	v_add_u32_e32 v176, s73, v1
	ds_read_b128 v[148:151], v160
	ds_read_b128 v[152:155], v160 offset:1024
	ds_read_b128 v[156:159], v160 offset:2048
	ds_read_b128 v[160:163], v160 offset:3072
	ds_read_b128 v[164:167], v176
	ds_read_b128 v[168:171], v176 offset:1024
	ds_read_b128 v[172:175], v176 offset:2048
	ds_read_b128 v[176:179], v176 offset:3072
	s_mov_b32 m0, s54
	v_lshl_add_u64 v[218:219], v[216:217], 0, s[12:13]
	ds_read_b128 v[180:183], v146 offset:32768
	ds_read_b128 v[188:191], v146 offset:33792
	ds_read_b128 v[192:195], v146 offset:34816
	ds_read_b128 v[196:199], v146 offset:35840
	ds_read_b128 v[200:203], v146 offset:36864
	ds_read_b128 v[204:207], v146 offset:37888
	ds_read_b128 v[208:211], v146 offset:38912
	ds_read_b128 v[212:215], v146 offset:39936
	global_load_lds_dwordx4 v[218:219], off
	v_lshl_add_u64 v[216:217], v[216:217], 0, s[14:15]
	s_mov_b32 m0, s55
	s_nop 0
	global_load_lds_dwordx4 v[216:217], off
	s_waitcnt vmcnt(8)
	s_waitcnt lgkmcnt(0)
	s_barrier
	s_setprio 1
	s_waitcnt lgkmcnt(0)
	v_mfma_f32_16x16x32_bf16 v[126:129], v[148:151], v[180:183], v[126:129]
	v_mfma_f32_16x16x32_bf16 v[110:113], v[148:151], v[192:195], v[110:113]
	v_mfma_f32_16x16x32_bf16 v[94:97], v[148:151], v[200:203], v[94:97]
	v_mfma_f32_16x16x32_bf16 v[78:81], v[148:151], v[208:211], v[78:81]
	v_mfma_f32_16x16x32_bf16 v[122:125], v[156:159], v[180:183], v[122:125]
	v_mfma_f32_16x16x32_bf16 v[106:109], v[156:159], v[192:195], v[106:109]
	v_mfma_f32_16x16x32_bf16 v[90:93], v[156:159], v[200:203], v[90:93]
	v_mfma_f32_16x16x32_bf16 v[74:77], v[156:159], v[208:211], v[74:77]
	v_mfma_f32_16x16x32_bf16 v[126:129], v[152:155], v[188:191], v[126:129]
	v_mfma_f32_16x16x32_bf16 v[110:113], v[152:155], v[196:199], v[110:113]
	v_mfma_f32_16x16x32_bf16 v[94:97], v[152:155], v[204:207], v[94:97]
	v_mfma_f32_16x16x32_bf16 v[78:81], v[152:155], v[212:215], v[78:81]
	v_mfma_f32_16x16x32_bf16 v[122:125], v[160:163], v[188:191], v[122:125]
	v_mfma_f32_16x16x32_bf16 v[106:109], v[160:163], v[196:199], v[106:109]
	v_mfma_f32_16x16x32_bf16 v[90:93], v[160:163], v[204:207], v[90:93]
	v_mfma_f32_16x16x32_bf16 v[74:77], v[160:163], v[212:215], v[74:77]
	s_setprio 0
	s_setprio 1
	v_mfma_f32_16x16x32_bf16 v[118:121], v[164:167], v[180:183], v[118:121]
	v_mfma_f32_16x16x32_bf16 v[102:105], v[164:167], v[192:195], v[102:105]
	v_mfma_f32_16x16x32_bf16 v[86:89], v[164:167], v[200:203], v[86:89]
	v_mfma_f32_16x16x32_bf16 v[70:73], v[164:167], v[208:211], v[70:73]
	v_mfma_f32_16x16x32_bf16 v[114:117], v[172:175], v[180:183], v[114:117]
	v_mfma_f32_16x16x32_bf16 v[98:101], v[172:175], v[192:195], v[98:101]
	v_mfma_f32_16x16x32_bf16 v[82:85], v[172:175], v[200:203], v[82:85]
	v_mfma_f32_16x16x32_bf16 v[66:69], v[172:175], v[208:211], v[66:69]
	v_mfma_f32_16x16x32_bf16 v[118:121], v[168:171], v[188:191], v[118:121]
	v_mfma_f32_16x16x32_bf16 v[102:105], v[168:171], v[196:199], v[102:105]
	v_mfma_f32_16x16x32_bf16 v[86:89], v[168:171], v[204:207], v[86:89]
	v_mfma_f32_16x16x32_bf16 v[70:73], v[168:171], v[212:215], v[70:73]
	v_mfma_f32_16x16x32_bf16 v[114:117], v[176:179], v[188:191], v[114:117]
	v_mfma_f32_16x16x32_bf16 v[98:101], v[176:179], v[196:199], v[98:101]
	v_mfma_f32_16x16x32_bf16 v[82:85], v[176:179], v[204:207], v[82:85]
	v_mfma_f32_16x16x32_bf16 v[66:69], v[176:179], v[212:215], v[66:69]
	s_setprio 0
	s_barrier
; __device__ __forceinline__ unsigned cvtpk(float lo, float hi) { f32x2 v = {lo, hi}; bf16x2_t b = __builtin_convertvector(v, bf16x2_t); return __builtin_bit_cast(unsigned, b); }
; #define PG8_STAGE(bufoff, gbase, voff) do { _Pragma("unroll") for (int _i = 0; _i < 2; ++_i) \
;         __builtin_amdgcn_global_load_lds((const unsigned*)((const char*)(gbase) + (size_t)_i * p##voff + (voff)), (LAS unsigned*)(lds + (bufoff) + ldsw + _i * 8192), 16, 0, 0); } while (0)
; #define PG8_LDA(dst, b, h) do { _Pragma("unroll") for (int m = 0; m < 4; ++m) _Pragma("unroll") for (int k = 0; k < 2; ++k) dst[m][k] = *(const LAS bf16x8*)(lds + PG8_SA(b, h) + aoff + m * 2048 + k * 1024); } while (0)
; #define PG8_WAIT_V(n) asm volatile("s_waitcnt vmcnt(" #n ")" ::: "memory")
; #define PG8_WAIT_L(n) asm volatile("s_waitcnt lgkmcnt(" #n ")" ::: "memory")
; #define PG8_BAR __builtin_amdgcn_s_barrier()
; #define PG8_SCHED __builtin_amdgcn_sched_barrier(0)
;     ...
;             PG8_LDA(At, 1, 1); PG8_STAGE(PG8_SB(1, 0), b3, voffB); PG8_STAGE(PG8_SB(1, 1), b3 + hstepB, voffB); PG8_STAGE(PG8_SA(1, 0), a3, voffA);
;             PG8_WAIT_V(8); PG8_WAIT_L(0); PG8_BAR; PG8_MMA(1, 0, At, B0); PG8_MMA(1, 1, At, B1); PG8_BAR; PG8_SCHED;
;         }
;     __device__ __forceinline__ void operator()(const Acc& acc, const Unit& u, int wr, int wc, int fr, int fq) const {
;         { const int ln = (int)__builtin_amdgcn_mbcnt_hi(~0u, __builtin_amdgcn_mbcnt_lo(~0u, 0u)); fr = ln & 15; fq = ln >> 4; }
;         const int rl = wr * 64 + fr, kt0 = u.pn * 4 + (wc >> 1), cl = (wc & 1) * 32 + 8 * fq;
; #pragma unroll
;         for (int ai = 0; ai < 2; ++ai)
; #pragma unroll
;             for (int m = 0; m < 4; ++m) { bf16_t* rp = O + (((size_t)u.pm * (DFF / 64) + kt0) * 256 + (rl + ai * 128 + m * 16)) * 64 + cl;
; #pragma unroll
;                 for (int bj = 0; bj < 2; ++bj) { f32x4 v0 = acc[ai][bj][m][0], v1 = acc[ai][bj][m][1];
; #pragma unroll
;                     for (int e = 0; e < 4; ++e) { const float a = fmaxf(v0[e], 0.f), b = fmaxf(v1[e], 0.f); v0[e] = a * a; v1[e] = b * b; }
;                     u32x4 w; w.x = cvtpk(v0[0], v0[1]); w.y = cvtpk(v0[2], v0[3]); w.z = cvtpk(v1[0], v1[1]); w.w = cvtpk(v1[2], v1[3]);
;                     *(u32x4*)(rp + (size_t)bj * 2 * 256 * 64) = w; } }
	s_add_i32 s72, s72, s50
	v_lshl_add_u64 v[216:217], v[184:185], 0, s[18:19]
	s_mov_b32 m0, s72
	ds_read_b128 v[180:183], v146 offset:49152
	ds_read_b128 v[188:191], v146 offset:50176
	ds_read_b128 v[192:195], v146 offset:51200
	ds_read_b128 v[196:199], v146 offset:52224
	ds_read_b128 v[200:203], v146 offset:53248
	ds_read_b128 v[204:207], v146 offset:54272
	ds_read_b128 v[208:211], v146 offset:55296
	ds_read_b128 v[212:215], v146 offset:56320
	global_load_lds_dwordx4 v[216:217], off
	v_lshl_add_u64 v[216:217], v[184:185], 0, s[20:21]
	s_add_i32 m0, s72, 0x2000
	s_add_i32 s72, s73, s50
	global_load_lds_dwordx4 v[216:217], off
	v_lshl_add_u64 v[216:217], v[184:185], 0, s[22:23]
	s_mov_b32 m0, s72
	v_lshl_add_u64 v[184:185], v[184:185], 0, s[24:25]
	global_load_lds_dwordx4 v[216:217], off
	s_add_i32 m0, s72, 0x2000
	s_nop 0
	global_load_lds_dwordx4 v[184:185], off
	v_lshl_add_u64 v[184:185], s[46:47], 0, v[130:131]
	s_mov_b32 m0, s58
	s_nop 0
	global_load_lds_dwordx4 v[184:185], off
	v_lshl_add_u64 v[184:185], v[184:185], 0, s[10:11]
	s_mov_b32 m0, s59
	s_nop 0
	global_load_lds_dwordx4 v[184:185], off
	s_waitcnt vmcnt(8)
	s_waitcnt lgkmcnt(0)
	s_barrier
	s_setprio 1
	s_waitcnt lgkmcnt(0)
	v_mfma_f32_16x16x32_bf16 v[62:65], v[148:151], v[180:183], v[62:65]
	v_mfma_f32_16x16x32_bf16 v[46:49], v[148:151], v[192:195], v[46:49]
	v_mfma_f32_16x16x32_bf16 v[30:33], v[148:151], v[200:203], v[30:33]
	v_mfma_f32_16x16x32_bf16 v[14:17], v[148:151], v[208:211], v[14:17]
	v_mfma_f32_16x16x32_bf16 v[58:61], v[156:159], v[180:183], v[58:61]
	v_mfma_f32_16x16x32_bf16 v[42:45], v[156:159], v[192:195], v[42:45]
	v_mfma_f32_16x16x32_bf16 v[26:29], v[156:159], v[200:203], v[26:29]
	v_mfma_f32_16x16x32_bf16 v[10:13], v[156:159], v[208:211], v[10:13]
	v_mfma_f32_16x16x32_bf16 v[62:65], v[152:155], v[188:191], v[62:65]
	v_mfma_f32_16x16x32_bf16 v[46:49], v[152:155], v[196:199], v[46:49]
	v_mfma_f32_16x16x32_bf16 v[30:33], v[152:155], v[204:207], v[30:33]
	v_mfma_f32_16x16x32_bf16 v[14:17], v[152:155], v[212:215], v[14:17]
	v_mfma_f32_16x16x32_bf16 v[58:61], v[160:163], v[188:191], v[58:61]
	v_mfma_f32_16x16x32_bf16 v[42:45], v[160:163], v[196:199], v[42:45]
	v_mfma_f32_16x16x32_bf16 v[26:29], v[160:163], v[204:207], v[26:29]
	v_mfma_f32_16x16x32_bf16 v[10:13], v[160:163], v[212:215], v[10:13]
	s_setprio 0
	s_setprio 1
	v_mfma_f32_16x16x32_bf16 v[54:57], v[164:167], v[180:183], v[54:57]
	v_mfma_f32_16x16x32_bf16 v[38:41], v[164:167], v[192:195], v[38:41]
	v_mfma_f32_16x16x32_bf16 v[22:25], v[164:167], v[200:203], v[22:25]
	v_mfma_f32_16x16x32_bf16 v[6:9], v[164:167], v[208:211], v[6:9]
	v_mfma_f32_16x16x32_bf16 v[50:53], v[172:175], v[180:183], v[50:53]
	v_mfma_f32_16x16x32_bf16 v[34:37], v[172:175], v[192:195], v[34:37]
	v_mfma_f32_16x16x32_bf16 v[18:21], v[172:175], v[200:203], v[18:21]
	v_mfma_f32_16x16x32_bf16 v[2:5], v[172:175], v[208:211], v[2:5]
	v_mfma_f32_16x16x32_bf16 v[54:57], v[168:171], v[188:191], v[54:57]
	v_mfma_f32_16x16x32_bf16 v[38:41], v[168:171], v[196:199], v[38:41]
	v_mfma_f32_16x16x32_bf16 v[22:25], v[168:171], v[204:207], v[22:25]
	v_mfma_f32_16x16x32_bf16 v[6:9], v[168:171], v[212:215], v[6:9]
	v_mfma_f32_16x16x32_bf16 v[50:53], v[176:179], v[188:191], v[50:53]
	v_mfma_f32_16x16x32_bf16 v[34:37], v[176:179], v[196:199], v[34:37]
	v_mfma_f32_16x16x32_bf16 v[18:21], v[176:179], v[204:207], v[18:21]
	v_mfma_f32_16x16x32_bf16 v[2:5], v[176:179], v[212:215], v[2:5]
	s_setprio 0
	s_barrier
	s_add_i32 s71, s71, 2
	s_add_u32 s69, s69, 0x100
	s_addc_u32 s70, s70, 0
	s_add_u32 s44, s44, 0x10000
	s_addc_u32 s45, s45, 0
	s_cmp_gt_u32 s71, 61
	s_cbranch_scc0 .LBB0_1206
	s_lshl_b32 s29, s41, 2
	s_or_b32 s42, s29, s61
	s_ashr_i32 s41, s40, 31
	s_ashr_i32 s43, s42, 31
	s_lshl_b64 s[40:41], s[40:41], 16
	s_lshl_b64 s[42:43], s[42:43], 8
	s_add_u32 s40, s42, s40
	v_lshrrev_b32_e32 v142, 1, v147
	s_addc_u32 s41, s43, s41
	v_and_b32_e32 v150, 56, v142
	v_lshl_add_u64 v[142:143], s[40:41], 0, v[134:135]
	v_max_f32_e32 v122, v122, v122
	v_max_f32_e32 v123, v123, v123
	v_lshlrev_b64 v[142:143], 7, v[142:143]
	v_max_f32_e32 v122, 0, v122
	v_max_f32_e32 v123, 0, v123
	v_lshl_add_u64 v[148:149], s[16:17], 0, v[142:143]
	v_add_lshl_u32 v142, v150, s62, 1
	v_pk_mul_f32 v[150:151], v[122:123], v[122:123]
	v_max_f32_e32 v123, v124, v124
	v_max_f32_e32 v126, v126, v126
	v_max_f32_e32 v127, v127, v127
	v_max_f32_e32 v122, v128, v128
	v_max_f32_e32 v124, 0, v123
	v_max_f32_e32 v123, v129, v129
	v_max_f32_e32 v125, v125, v125
	v_max_f32_e32 v126, 0, v126
	v_max_f32_e32 v127, 0, v127
	v_max_f32_e32 v122, 0, v122
	v_max_f32_e32 v123, 0, v123
	v_max_f32_e32 v125, 0, v125
	v_mov_b32_e32 v143, v135
	v_pk_mul_f32 v[126:127], v[126:127], v[126:127]
	v_pk_mul_f32 v[128:129], v[122:123], v[122:123]
	v_pk_mul_f32 v[152:153], v[124:125], v[124:125]
	v_max_f32_e32 v114, v114, v114
	v_max_f32_e32 v115, v115, v115
	v_lshl_add_u64 v[148:149], v[148:149], 0, v[142:143]
	v_cvt_pk_bf16_f32 v122, v126, v127
	v_cvt_pk_bf16_f32 v123, v128, v129
	v_cvt_pk_bf16_f32 v124, v150, v151
	v_cvt_pk_bf16_f32 v125, v152, v153
	v_max_f32_e32 v114, 0, v114
	v_max_f32_e32 v115, 0, v115
	global_store_dwordx4 v[148:149], v[122:125], off
	v_max_f32_e32 v118, v118, v118
	v_max_f32_e32 v119, v119, v119
	v_pk_mul_f32 v[122:123], v[114:115], v[114:115]
	v_max_f32_e32 v115, v116, v116
	v_max_f32_e32 v118, 0, v118
	v_max_f32_e32 v119, 0, v119
	v_max_f32_e32 v114, v120, v120
	v_max_f32_e32 v116, 0, v115
	v_max_f32_e32 v115, v121, v121
	v_max_f32_e32 v117, v117, v117
	v_pk_mul_f32 v[118:119], v[118:119], v[118:119]
	v_max_f32_e32 v114, 0, v114
	v_max_f32_e32 v115, 0, v115
	v_max_f32_e32 v117, 0, v117
; __device__ __forceinline__ unsigned cvtpk(float lo, float hi) { f32x2 v = {lo, hi}; bf16x2_t b = __builtin_convertvector(v, bf16x2_t); return __builtin_bit_cast(unsigned, b); }
;     __device__ __forceinline__ void operator()(const Acc& acc, const Unit& u, int wr, int wc, int fr, int fq) const {
;         { const int ln = (int)__builtin_amdgcn_mbcnt_hi(~0u, __builtin_amdgcn_mbcnt_lo(~0u, 0u)); fr = ln & 15; fq = ln >> 4; }
;         const int rl = wr * 64 + fr, kt0 = u.pn * 4 + (wc >> 1), cl = (wc & 1) * 32 + 8 * fq;
; #pragma unroll
;         for (int ai = 0; ai < 2; ++ai)
; #pragma unroll
;             for (int m = 0; m < 4; ++m) { bf16_t* rp = O + (((size_t)u.pm * (DFF / 64) + kt0) * 256 + (rl + ai * 128 + m * 16)) * 64 + cl;
; #pragma unroll
;                 for (int bj = 0; bj < 2; ++bj) { f32x4 v0 = acc[ai][bj][m][0], v1 = acc[ai][bj][m][1];
; #pragma unroll
;                     for (int e = 0; e < 4; ++e) { const float a = fmaxf(v0[e], 0.f), b = fmaxf(v1[e], 0.f); v0[e] = a * a; v1[e] = b * b; }
;                     u32x4 w; w.x = cvtpk(v0[0], v0[1]); w.y = cvtpk(v0[2], v0[3]); w.z = cvtpk(v1[0], v1[1]); w.w = cvtpk(v1[2], v1[3]);
;                     *(u32x4*)(rp + (size_t)bj * 2 * 256 * 64) = w; } }
	v_pk_mul_f32 v[120:121], v[114:115], v[114:115]
	v_pk_mul_f32 v[124:125], v[116:117], v[116:117]
	v_cvt_pk_bf16_f32 v114, v118, v119
	v_add_co_u32_e32 v118, vcc, s57, v148
	v_max_f32_e32 v106, v106, v106
	v_max_f32_e32 v107, v107, v107
	v_cvt_pk_bf16_f32 v115, v120, v121
	v_cvt_pk_bf16_f32 v116, v122, v123
	v_cvt_pk_bf16_f32 v117, v124, v125
	v_addc_co_u32_e32 v119, vcc, 0, v149, vcc
	v_max_f32_e32 v106, 0, v106
	v_max_f32_e32 v107, 0, v107
	global_store_dwordx4 v[118:119], v[114:117], off
	v_max_f32_e32 v110, v110, v110
	v_max_f32_e32 v111, v111, v111
	v_or_b32_e32 v114, 16, v134
	v_mov_b32_e32 v115, v135
	v_pk_mul_f32 v[116:117], v[106:107], v[106:107]
	v_max_f32_e32 v107, v108, v108
	v_lshl_add_u64 v[114:115], s[40:41], 0, v[114:115]
	v_max_f32_e32 v106, v112, v112
	v_max_f32_e32 v108, 0, v107
	v_max_f32_e32 v107, v113, v113
	v_max_f32_e32 v109, v109, v109
	v_lshlrev_b64 v[114:115], 7, v[114:115]
	v_max_f32_e32 v110, 0, v110
	v_max_f32_e32 v111, 0, v111
	v_max_f32_e32 v106, 0, v106
	v_max_f32_e32 v107, 0, v107
	v_max_f32_e32 v109, 0, v109
	v_lshl_add_u64 v[114:115], s[16:17], 0, v[114:115]
	v_pk_mul_f32 v[110:111], v[110:111], v[110:111]
	v_pk_mul_f32 v[112:113], v[106:107], v[106:107]
	v_pk_mul_f32 v[118:119], v[108:109], v[108:109]
	v_max_f32_e32 v98, v98, v98
	v_max_f32_e32 v99, v99, v99
	v_lshl_add_u64 v[114:115], v[114:115], 0, v[142:143]
	v_cvt_pk_bf16_f32 v106, v110, v111
	v_cvt_pk_bf16_f32 v107, v112, v113
	v_cvt_pk_bf16_f32 v108, v116, v117
	v_cvt_pk_bf16_f32 v109, v118, v119
	v_max_f32_e32 v98, 0, v98
	v_max_f32_e32 v99, 0, v99
	global_store_dwordx4 v[114:115], v[106:109], off
	v_max_f32_e32 v102, v102, v102
	v_max_f32_e32 v103, v103, v103
	v_pk_mul_f32 v[106:107], v[98:99], v[98:99]
	v_max_f32_e32 v99, v100, v100
	v_max_f32_e32 v102, 0, v102
	v_max_f32_e32 v103, 0, v103
	v_max_f32_e32 v98, v104, v104
	v_max_f32_e32 v100, 0, v99
	v_max_f32_e32 v99, v105, v105
	v_max_f32_e32 v101, v101, v101
	v_pk_mul_f32 v[102:103], v[102:103], v[102:103]
	v_max_f32_e32 v98, 0, v98
	v_max_f32_e32 v99, 0, v99
	v_max_f32_e32 v101, 0, v101
	v_pk_mul_f32 v[104:105], v[98:99], v[98:99]
	v_pk_mul_f32 v[108:109], v[100:101], v[100:101]
	v_cvt_pk_bf16_f32 v98, v102, v103
	v_add_co_u32_e32 v102, vcc, s57, v114
	v_max_f32_e32 v90, v90, v90
	v_max_f32_e32 v91, v91, v91
	v_cvt_pk_bf16_f32 v99, v104, v105
	v_cvt_pk_bf16_f32 v100, v106, v107
	v_cvt_pk_bf16_f32 v101, v108, v109
	v_addc_co_u32_e32 v103, vcc, 0, v115, vcc
	v_max_f32_e32 v90, 0, v90
	v_max_f32_e32 v91, 0, v91
	global_store_dwordx4 v[102:103], v[98:101], off
	v_max_f32_e32 v94, v94, v94
	v_max_f32_e32 v95, v95, v95
	v_or_b32_e32 v98, 32, v134
	v_mov_b32_e32 v99, v135
	v_pk_mul_f32 v[100:101], v[90:91], v[90:91]
	v_max_f32_e32 v91, v92, v92
	v_lshl_add_u64 v[98:99], s[40:41], 0, v[98:99]
	v_max_f32_e32 v90, v96, v96
	v_max_f32_e32 v92, 0, v91
	v_max_f32_e32 v91, v97, v97
	v_max_f32_e32 v93, v93, v93
	v_lshlrev_b64 v[98:99], 7, v[98:99]
	v_max_f32_e32 v94, 0, v94
	v_max_f32_e32 v95, 0, v95
	v_max_f32_e32 v90, 0, v90
	v_max_f32_e32 v91, 0, v91
	v_max_f32_e32 v93, 0, v93
	v_lshl_add_u64 v[98:99], s[16:17], 0, v[98:99]
	v_pk_mul_f32 v[94:95], v[94:95], v[94:95]
	v_pk_mul_f32 v[96:97], v[90:91], v[90:91]
	v_pk_mul_f32 v[102:103], v[92:93], v[92:93]
	v_max_f32_e32 v82, v82, v82
	v_max_f32_e32 v83, v83, v83
	v_lshl_add_u64 v[98:99], v[98:99], 0, v[142:143]
	v_cvt_pk_bf16_f32 v90, v94, v95
	v_cvt_pk_bf16_f32 v91, v96, v97
	v_cvt_pk_bf16_f32 v92, v100, v101
	v_cvt_pk_bf16_f32 v93, v102, v103
	v_max_f32_e32 v82, 0, v82
	v_max_f32_e32 v83, 0, v83
	global_store_dwordx4 v[98:99], v[90:93], off
	v_max_f32_e32 v86, v86, v86
	v_max_f32_e32 v87, v87, v87
	v_pk_mul_f32 v[90:91], v[82:83], v[82:83]
	v_max_f32_e32 v83, v84, v84
	v_max_f32_e32 v86, 0, v86
	v_max_f32_e32 v87, 0, v87
	v_max_f32_e32 v82, v88, v88
	v_max_f32_e32 v84, 0, v83
	v_max_f32_e32 v83, v89, v89
	v_max_f32_e32 v85, v85, v85
	v_pk_mul_f32 v[86:87], v[86:87], v[86:87]
	v_max_f32_e32 v82, 0, v82
	v_max_f32_e32 v83, 0, v83
	v_max_f32_e32 v85, 0, v85
	v_pk_mul_f32 v[88:89], v[82:83], v[82:83]
	v_pk_mul_f32 v[92:93], v[84:85], v[84:85]
	v_cvt_pk_bf16_f32 v82, v86, v87
	v_add_co_u32_e32 v86, vcc, s57, v98
	v_max_f32_e32 v74, v74, v74
	v_max_f32_e32 v75, v75, v75
	v_cvt_pk_bf16_f32 v83, v88, v89
	v_cvt_pk_bf16_f32 v84, v90, v91
	v_cvt_pk_bf16_f32 v85, v92, v93
	v_addc_co_u32_e32 v87, vcc, 0, v99, vcc
	v_max_f32_e32 v74, 0, v74
	v_max_f32_e32 v75, 0, v75
	global_store_dwordx4 v[86:87], v[82:85], off
	v_max_f32_e32 v78, v78, v78
	v_max_f32_e32 v79, v79, v79
	v_or_b32_e32 v82, 48, v134
	v_mov_b32_e32 v83, v135
	v_pk_mul_f32 v[84:85], v[74:75], v[74:75]
	v_max_f32_e32 v75, v76, v76
	v_lshl_add_u64 v[82:83], s[40:41], 0, v[82:83]
	v_max_f32_e32 v74, v80, v80
	v_max_f32_e32 v76, 0, v75
	v_max_f32_e32 v75, v81, v81
	v_max_f32_e32 v77, v77, v77
	v_lshlrev_b64 v[82:83], 7, v[82:83]
	v_max_f32_e32 v78, 0, v78
	v_max_f32_e32 v79, 0, v79
	v_max_f32_e32 v74, 0, v74
	v_max_f32_e32 v75, 0, v75
	v_max_f32_e32 v77, 0, v77
	v_lshl_add_u64 v[82:83], s[16:17], 0, v[82:83]
	v_pk_mul_f32 v[78:79], v[78:79], v[78:79]
	v_pk_mul_f32 v[80:81], v[74:75], v[74:75]
	v_pk_mul_f32 v[86:87], v[76:77], v[76:77]
	v_max_f32_e32 v66, v66, v66
	v_max_f32_e32 v67, v67, v67
	v_lshl_add_u64 v[82:83], v[82:83], 0, v[142:143]
	v_cvt_pk_bf16_f32 v74, v78, v79
	v_cvt_pk_bf16_f32 v75, v80, v81
	v_cvt_pk_bf16_f32 v76, v84, v85
	v_cvt_pk_bf16_f32 v77, v86, v87
	v_max_f32_e32 v66, 0, v66
	v_max_f32_e32 v67, 0, v67
	global_store_dwordx4 v[82:83], v[74:77], off
	v_max_f32_e32 v70, v70, v70
	v_max_f32_e32 v71, v71, v71
	v_pk_mul_f32 v[74:75], v[66:67], v[66:67]
	v_max_f32_e32 v67, v68, v68
; __device__ __forceinline__ unsigned cvtpk(float lo, float hi) { f32x2 v = {lo, hi}; bf16x2_t b = __builtin_convertvector(v, bf16x2_t); return __builtin_bit_cast(unsigned, b); }
;     __device__ __forceinline__ void operator()(const Acc& acc, const Unit& u, int wr, int wc, int fr, int fq) const {
;     ...
;         for (int ai = 0; ai < 2; ++ai)
; #pragma unroll
;             for (int m = 0; m < 4; ++m) { bf16_t* rp = O + (((size_t)u.pm * (DFF / 64) + kt0) * 256 + (rl + ai * 128 + m * 16)) * 64 + cl;
; #pragma unroll
;                 for (int bj = 0; bj < 2; ++bj) { f32x4 v0 = acc[ai][bj][m][0], v1 = acc[ai][bj][m][1];
; #pragma unroll
;                     for (int e = 0; e < 4; ++e) { const float a = fmaxf(v0[e], 0.f), b = fmaxf(v1[e], 0.f); v0[e] = a * a; v1[e] = b * b; }
;                     u32x4 w; w.x = cvtpk(v0[0], v0[1]); w.y = cvtpk(v0[2], v0[3]); w.z = cvtpk(v1[0], v1[1]); w.w = cvtpk(v1[2], v1[3]);
;                     *(u32x4*)(rp + (size_t)bj * 2 * 256 * 64) = w; } }
	v_max_f32_e32 v70, 0, v70
	v_max_f32_e32 v71, 0, v71
	v_max_f32_e32 v66, v72, v72
	v_max_f32_e32 v68, 0, v67
	v_max_f32_e32 v67, v73, v73
	v_max_f32_e32 v69, v69, v69
	v_pk_mul_f32 v[70:71], v[70:71], v[70:71]
	v_max_f32_e32 v66, 0, v66
	v_max_f32_e32 v67, 0, v67
	v_max_f32_e32 v69, 0, v69
	v_pk_mul_f32 v[72:73], v[66:67], v[66:67]
	v_pk_mul_f32 v[76:77], v[68:69], v[68:69]
	v_cvt_pk_bf16_f32 v66, v70, v71
	v_add_co_u32_e32 v70, vcc, s57, v82
	v_max_f32_e32 v58, v58, v58
	v_max_f32_e32 v59, v59, v59
	v_cvt_pk_bf16_f32 v67, v72, v73
	v_cvt_pk_bf16_f32 v68, v74, v75
	v_cvt_pk_bf16_f32 v69, v76, v77
	v_addc_co_u32_e32 v71, vcc, 0, v83, vcc
	v_max_f32_e32 v58, 0, v58
	v_max_f32_e32 v59, 0, v59
	global_store_dwordx4 v[70:71], v[66:69], off
	v_max_f32_e32 v62, v62, v62
	v_max_f32_e32 v63, v63, v63
	v_add_u32_e32 v66, 0x80, v134
	v_mov_b32_e32 v67, v135
	v_pk_mul_f32 v[68:69], v[58:59], v[58:59]
	v_max_f32_e32 v59, v60, v60
	v_lshl_add_u64 v[66:67], s[40:41], 0, v[66:67]
	v_max_f32_e32 v58, v64, v64
	v_max_f32_e32 v60, 0, v59
	v_max_f32_e32 v59, v65, v65
	v_max_f32_e32 v61, v61, v61
	v_lshlrev_b64 v[66:67], 7, v[66:67]
	v_max_f32_e32 v62, 0, v62
	v_max_f32_e32 v63, 0, v63
	v_max_f32_e32 v58, 0, v58
	v_max_f32_e32 v59, 0, v59
	v_max_f32_e32 v61, 0, v61
	v_lshl_add_u64 v[66:67], s[16:17], 0, v[66:67]
	v_pk_mul_f32 v[62:63], v[62:63], v[62:63]
	v_pk_mul_f32 v[64:65], v[58:59], v[58:59]
	v_pk_mul_f32 v[70:71], v[60:61], v[60:61]
	v_max_f32_e32 v50, v50, v50
	v_max_f32_e32 v51, v51, v51
	v_lshl_add_u64 v[66:67], v[66:67], 0, v[142:143]
	v_cvt_pk_bf16_f32 v58, v62, v63
	v_cvt_pk_bf16_f32 v59, v64, v65
	v_cvt_pk_bf16_f32 v60, v68, v69
	v_cvt_pk_bf16_f32 v61, v70, v71
	v_max_f32_e32 v50, 0, v50
	v_max_f32_e32 v51, 0, v51
	global_store_dwordx4 v[66:67], v[58:61], off
	v_max_f32_e32 v54, v54, v54
	v_max_f32_e32 v55, v55, v55
	v_pk_mul_f32 v[58:59], v[50:51], v[50:51]
	v_max_f32_e32 v51, v52, v52
	v_max_f32_e32 v54, 0, v54
	v_max_f32_e32 v55, 0, v55
	v_max_f32_e32 v50, v56, v56
	v_max_f32_e32 v52, 0, v51
	v_max_f32_e32 v51, v57, v57
	v_max_f32_e32 v53, v53, v53
	v_pk_mul_f32 v[54:55], v[54:55], v[54:55]
	v_max_f32_e32 v50, 0, v50
	v_max_f32_e32 v51, 0, v51
	v_max_f32_e32 v53, 0, v53
	v_pk_mul_f32 v[56:57], v[50:51], v[50:51]
	v_pk_mul_f32 v[60:61], v[52:53], v[52:53]
	v_cvt_pk_bf16_f32 v50, v54, v55
	v_add_co_u32_e32 v54, vcc, s57, v66
	v_max_f32_e32 v42, v42, v42
	v_max_f32_e32 v43, v43, v43
	v_cvt_pk_bf16_f32 v51, v56, v57
	v_cvt_pk_bf16_f32 v52, v58, v59
	v_cvt_pk_bf16_f32 v53, v60, v61
	v_addc_co_u32_e32 v55, vcc, 0, v67, vcc
	v_max_f32_e32 v42, 0, v42
	v_max_f32_e32 v43, 0, v43
	global_store_dwordx4 v[54:55], v[50:53], off
	v_max_f32_e32 v46, v46, v46
	v_max_f32_e32 v47, v47, v47
	v_add_u32_e32 v50, 0x90, v134
	v_mov_b32_e32 v51, v135
	v_pk_mul_f32 v[52:53], v[42:43], v[42:43]
	v_max_f32_e32 v43, v44, v44
	v_lshl_add_u64 v[50:51], s[40:41], 0, v[50:51]
	v_max_f32_e32 v42, v48, v48
	v_max_f32_e32 v44, 0, v43
	v_max_f32_e32 v43, v49, v49
	v_max_f32_e32 v45, v45, v45
	v_lshlrev_b64 v[50:51], 7, v[50:51]
	v_max_f32_e32 v46, 0, v46
	v_max_f32_e32 v47, 0, v47
	v_max_f32_e32 v42, 0, v42
	v_max_f32_e32 v43, 0, v43
	v_max_f32_e32 v45, 0, v45
	v_lshl_add_u64 v[50:51], s[16:17], 0, v[50:51]
	v_pk_mul_f32 v[46:47], v[46:47], v[46:47]
	v_pk_mul_f32 v[48:49], v[42:43], v[42:43]
	v_pk_mul_f32 v[54:55], v[44:45], v[44:45]
	v_max_f32_e32 v34, v34, v34
	v_max_f32_e32 v35, v35, v35
	v_lshl_add_u64 v[50:51], v[50:51], 0, v[142:143]
	v_cvt_pk_bf16_f32 v42, v46, v47
	v_cvt_pk_bf16_f32 v43, v48, v49
	v_cvt_pk_bf16_f32 v44, v52, v53
	v_cvt_pk_bf16_f32 v45, v54, v55
	v_max_f32_e32 v34, 0, v34
	v_max_f32_e32 v35, 0, v35
	global_store_dwordx4 v[50:51], v[42:45], off
	v_max_f32_e32 v38, v38, v38
	v_max_f32_e32 v39, v39, v39
	v_pk_mul_f32 v[42:43], v[34:35], v[34:35]
	v_max_f32_e32 v35, v36, v36
	v_max_f32_e32 v38, 0, v38
	v_max_f32_e32 v39, 0, v39
	v_max_f32_e32 v34, v40, v40
	v_max_f32_e32 v36, 0, v35
	v_max_f32_e32 v35, v41, v41
	v_max_f32_e32 v37, v37, v37
	v_pk_mul_f32 v[38:39], v[38:39], v[38:39]
	v_max_f32_e32 v34, 0, v34
	v_max_f32_e32 v35, 0, v35
	v_max_f32_e32 v37, 0, v37
	v_pk_mul_f32 v[40:41], v[34:35], v[34:35]
	v_pk_mul_f32 v[44:45], v[36:37], v[36:37]
	v_cvt_pk_bf16_f32 v34, v38, v39
; __device__ __forceinline__ unsigned cvtpk(float lo, float hi) { f32x2 v = {lo, hi}; bf16x2_t b = __builtin_convertvector(v, bf16x2_t); return __builtin_bit_cast(unsigned, b); }
; #define PG8_WAIT_V(n) asm volatile("s_waitcnt vmcnt(" #n ")" ::: "memory")
; #define PG8_BAR __builtin_amdgcn_s_barrier()
;     ...
;         if (!has_next) break;
; #pragma unroll
;         for (int a = 0; a < 2; ++a)
; #pragma unroll
;             for (int b = 0; b < 2; ++b)
; #pragma unroll
;                 for (int m = 0; m < 4; ++m)
; #pragma unroll
;                     for (int n = 0; n < 2; ++n) acc[a][b][m][n] = (f32x4){0.f, 0.f, 0.f, 0.f};
;         cur = nxt; cA = nA; cB = nB; ++ui;
;         if constexpr (ALIGN) { if (wr == 1) PG8_BAR; }
;     }
;     PG8_WAIT_V(0);
;     if constexpr (!ALIGN) { if (wr == 0) PG8_BAR; }
;     PG8_BAR;
;     __device__ __forceinline__ void operator()(const Acc& acc, const Unit& u, int wr, int wc, int fr, int fq) const {
;     ...
;         for (int ai = 0; ai < 2; ++ai)
; #pragma unroll
;             for (int m = 0; m < 4; ++m) { bf16_t* rp = O + (((size_t)u.pm * (DFF / 64) + kt0) * 256 + (rl + ai * 128 + m * 16)) * 64 + cl;
; #pragma unroll
;                 for (int bj = 0; bj < 2; ++bj) { f32x4 v0 = acc[ai][bj][m][0], v1 = acc[ai][bj][m][1];
; #pragma unroll
;                     for (int e = 0; e < 4; ++e) { const float a = fmaxf(v0[e], 0.f), b = fmaxf(v1[e], 0.f); v0[e] = a * a; v1[e] = b * b; }
;                     u32x4 w; w.x = cvtpk(v0[0], v0[1]); w.y = cvtpk(v0[2], v0[3]); w.z = cvtpk(v1[0], v1[1]); w.w = cvtpk(v1[2], v1[3]);
;                     *(u32x4*)(rp + (size_t)bj * 2 * 256 * 64) = w; } }
	v_add_co_u32_e32 v38, vcc, s57, v50
	v_max_f32_e32 v26, v26, v26
	v_max_f32_e32 v27, v27, v27
	v_cvt_pk_bf16_f32 v35, v40, v41
	v_cvt_pk_bf16_f32 v36, v42, v43
	v_cvt_pk_bf16_f32 v37, v44, v45
	v_addc_co_u32_e32 v39, vcc, 0, v51, vcc
	v_max_f32_e32 v26, 0, v26
	v_max_f32_e32 v27, 0, v27
	global_store_dwordx4 v[38:39], v[34:37], off
	v_max_f32_e32 v30, v30, v30
	v_max_f32_e32 v31, v31, v31
	v_add_u32_e32 v34, 0xa0, v134
	v_mov_b32_e32 v35, v135
	v_pk_mul_f32 v[36:37], v[26:27], v[26:27]
	v_max_f32_e32 v27, v28, v28
	v_lshl_add_u64 v[34:35], s[40:41], 0, v[34:35]
	v_max_f32_e32 v26, v32, v32
	v_max_f32_e32 v28, 0, v27
	v_max_f32_e32 v27, v33, v33
	v_max_f32_e32 v29, v29, v29
	v_lshlrev_b64 v[34:35], 7, v[34:35]
	v_max_f32_e32 v30, 0, v30
	v_max_f32_e32 v31, 0, v31
	v_max_f32_e32 v26, 0, v26
	v_max_f32_e32 v27, 0, v27
	v_max_f32_e32 v29, 0, v29
	v_lshl_add_u64 v[34:35], s[16:17], 0, v[34:35]
	v_pk_mul_f32 v[30:31], v[30:31], v[30:31]
	v_pk_mul_f32 v[32:33], v[26:27], v[26:27]
	v_pk_mul_f32 v[38:39], v[28:29], v[28:29]
	v_max_f32_e32 v18, v18, v18
	v_max_f32_e32 v19, v19, v19
	v_lshl_add_u64 v[34:35], v[34:35], 0, v[142:143]
	v_cvt_pk_bf16_f32 v26, v30, v31
	v_cvt_pk_bf16_f32 v27, v32, v33
	v_cvt_pk_bf16_f32 v28, v36, v37
	v_cvt_pk_bf16_f32 v29, v38, v39
	v_max_f32_e32 v18, 0, v18
	v_max_f32_e32 v19, 0, v19
	global_store_dwordx4 v[34:35], v[26:29], off
	v_max_f32_e32 v22, v22, v22
	v_max_f32_e32 v23, v23, v23
	v_pk_mul_f32 v[26:27], v[18:19], v[18:19]
	v_max_f32_e32 v19, v20, v20
	v_max_f32_e32 v22, 0, v22
	v_max_f32_e32 v23, 0, v23
	v_max_f32_e32 v18, v24, v24
	v_max_f32_e32 v20, 0, v19
	v_max_f32_e32 v19, v25, v25
	v_max_f32_e32 v21, v21, v21
	v_pk_mul_f32 v[22:23], v[22:23], v[22:23]
	v_max_f32_e32 v18, 0, v18
	v_max_f32_e32 v19, 0, v19
	v_max_f32_e32 v21, 0, v21
	v_pk_mul_f32 v[24:25], v[18:19], v[18:19]
	v_pk_mul_f32 v[28:29], v[20:21], v[20:21]
	v_cvt_pk_bf16_f32 v18, v22, v23
	v_add_co_u32_e32 v22, vcc, s57, v34
	v_max_f32_e32 v10, v10, v10
	v_max_f32_e32 v11, v11, v11
	v_cvt_pk_bf16_f32 v19, v24, v25
	v_cvt_pk_bf16_f32 v20, v26, v27
	v_cvt_pk_bf16_f32 v21, v28, v29
	v_addc_co_u32_e32 v23, vcc, 0, v35, vcc
	v_max_f32_e32 v10, 0, v10
	v_max_f32_e32 v11, 0, v11
	global_store_dwordx4 v[22:23], v[18:21], off
	v_max_f32_e32 v14, v14, v14
	v_max_f32_e32 v15, v15, v15
	v_add_u32_e32 v18, 0xb0, v134
	v_mov_b32_e32 v19, v135
	v_pk_mul_f32 v[20:21], v[10:11], v[10:11]
	v_max_f32_e32 v11, v12, v12
	v_lshl_add_u64 v[18:19], s[40:41], 0, v[18:19]
	v_max_f32_e32 v10, v16, v16
	v_max_f32_e32 v12, 0, v11
	v_max_f32_e32 v11, v17, v17
	v_max_f32_e32 v13, v13, v13
	v_lshlrev_b64 v[18:19], 7, v[18:19]
	v_max_f32_e32 v14, 0, v14
	v_max_f32_e32 v15, 0, v15
	v_max_f32_e32 v10, 0, v10
	v_max_f32_e32 v11, 0, v11
	v_max_f32_e32 v13, 0, v13
	v_lshl_add_u64 v[18:19], s[16:17], 0, v[18:19]
	v_pk_mul_f32 v[14:15], v[14:15], v[14:15]
	v_pk_mul_f32 v[16:17], v[10:11], v[10:11]
	v_pk_mul_f32 v[22:23], v[12:13], v[12:13]
	v_max_f32_e32 v2, v2, v2
	v_max_f32_e32 v3, v3, v3
	v_lshl_add_u64 v[18:19], v[18:19], 0, v[142:143]
	v_cvt_pk_bf16_f32 v10, v14, v15
	v_cvt_pk_bf16_f32 v11, v16, v17
	v_cvt_pk_bf16_f32 v12, v20, v21
	v_cvt_pk_bf16_f32 v13, v22, v23
	v_max_f32_e32 v2, 0, v2
	v_max_f32_e32 v3, 0, v3
	global_store_dwordx4 v[18:19], v[10:13], off
	v_max_f32_e32 v6, v6, v6
	v_max_f32_e32 v7, v7, v7
	v_pk_mul_f32 v[10:11], v[2:3], v[2:3]
	v_max_f32_e32 v3, v4, v4
	v_max_f32_e32 v6, 0, v6
	v_max_f32_e32 v7, 0, v7
	v_max_f32_e32 v2, v8, v8
	v_max_f32_e32 v4, 0, v3
	v_max_f32_e32 v3, v9, v9
	v_pk_mul_f32 v[6:7], v[6:7], v[6:7]
	v_max_f32_e32 v2, 0, v2
	v_max_f32_e32 v3, 0, v3
	v_max_f32_e32 v5, v5, v5
	v_max_f32_e32 v5, 0, v5
	v_pk_mul_f32 v[8:9], v[2:3], v[2:3]
	v_cvt_pk_bf16_f32 v2, v6, v7
	v_add_co_u32_e32 v6, vcc, 0x10000, v18
	v_pk_mul_f32 v[12:13], v[4:5], v[4:5]
	s_nop 0
	v_addc_co_u32_e32 v7, vcc, 0, v19, vcc
	v_cvt_pk_bf16_f32 v3, v8, v9
	v_cvt_pk_bf16_f32 v4, v10, v11
	v_cvt_pk_bf16_f32 v5, v12, v13
	s_and_b64 vcc, exec, s[2:3]
	s_mov_b32 s41, s28
	s_mov_b32 s40, s34
	s_mov_b64 s[44:45], s[38:39]
	s_mov_b64 s[42:43], s[36:37]
	global_store_dwordx4 v[6:7], v[2:5], off
	s_cbranch_vccz .LBB0_1199
	s_waitcnt vmcnt(0)
	s_cmpk_gt_u32 s33, 0xff
	s_cbranch_scc1 .LBB0_1210
	s_barrier

;     __device__ __forceinline__ size_t a_koff(int t) const { return (size_t)t * 128; }
;     __device__ __forceinline__ size_t a_koff(int t) const { return (size_t)t * 32768; }
; #define PG8_STAGE(bufoff, gbase, voff) do { _Pragma("unroll") for (int _i = 0; _i < 2; ++_i) \
;         __builtin_amdgcn_global_load_lds((const unsigned*)((const char*)(gbase) + (size_t)_i * p##voff + (voff)), (LAS unsigned*)(lds + (bufoff) + ldsw + _i * 8192), 16, 0, 0); } while (0)
; #define PG8_LDA(dst, b, h) do { _Pragma("unroll") for (int m = 0; m < 4; ++m) _Pragma("unroll") for (int k = 0; k < 2; ++k) dst[m][k] = *(const LAS bf16x8*)(lds + PG8_SA(b, h) + aoff + m * 2048 + k * 1024); } while (0)
; #define PG8_LDB(dst, b, h) do { _Pragma("unroll") for (int n = 0; n < 2; ++n) _Pragma("unroll") for (int k = 0; k < 2; ++k) dst[n][k] = *(const LAS bf16x8*)(lds + PG8_SB(b, h) + boff + n * 2048 + k * 1024); } while (0)
; #define PG8_WAIT_V(n) asm volatile("s_waitcnt vmcnt(" #n ")" ::: "memory")
; #define PG8_WAIT_L(n) asm volatile("s_waitcnt lgkmcnt(" #n ")" ::: "memory")
; #define PG8_BAR __builtin_amdgcn_s_barrier()
; #define PG8_SCHED __builtin_amdgcn_sched_barrier(0)
;     __device__ __forceinline__ size_t a_koff(int t) const { return ((size_t)(t >> 1) * 3072 + (size_t)(t & 1) * 64) * 2; }
;     __device__ __forceinline__ size_t a_koff(int t) const { return (size_t)t * 128; }
;     ...
;         for (int t = 0; t < nt; t += 2) {
;             const bool last = (t == nt - 2);
;             const char* a1 = cA + g.a_koff(t + 1);
;             const char* a2 = last ? nA : cA + g.a_koff(t + 2); const char* b2 = last ? nB : cB + (size_t)(t + 2) * kstep;
;             const char* a3 = last ? nA + g.a_koff(1) : cA + g.a_koff(t + 3); const char* b3 = b2 + kstep;
;             PG8_LDB(B0, 0, 0); PG8_LDB(B1, 0, 1); PG8_SCHED; PG8_LDA(At, 0, 0); PG8_STAGE(PG8_SA(1, 1), a1 + hstepA, voffA);
;             PG8_WAIT_V(8); PG8_WAIT_L(0); PG8_BAR; PG8_MMA(0, 0, At, B0); PG8_MMA(0, 1, At, B1); PG8_BAR; PG8_SCHED;
;             PG8_LDA(At, 0, 1); PG8_STAGE(PG8_SB(0, 0), b2, voffB); PG8_STAGE(PG8_SB(0, 1), b2 + hstepB, voffB); PG8_STAGE(PG8_SA(0, 0), a2, voffA);
;             PG8_WAIT_V(8); PG8_WAIT_L(0); PG8_BAR; PG8_MMA(1, 0, At, B0); PG8_MMA(1, 1, At, B1); PG8_BAR; PG8_SCHED;
.LBB0_1281:
	ds_read_b128 v[142:145], v188
	ds_read_b128 v[146:149], v188 offset:1024
	ds_read_b128 v[150:153], v188 offset:2048
	ds_read_b128 v[154:157], v188 offset:3072
	ds_read_b128 v[158:161], v189
	ds_read_b128 v[162:165], v189 offset:1024
	ds_read_b128 v[166:169], v189 offset:2048
	ds_read_b128 v[170:173], v189 offset:3072
	s_add_u32 s50, s44, s48
	s_addc_u32 s51, s45, s49
	s_add_u32 s83, s50, 0x10000
	s_addc_u32 s86, s51, 0
	s_add_u32 s50, s50, 0x18000
	s_addc_u32 s51, s51, 0
	s_cmp_eq_u32 s48, 0x7f0000
	s_cselect_b32 s51, s79, s51
	s_cselect_b32 s50, s78, s50
	s_cselect_b32 s85, s35, s81
	s_cselect_b32 s84, s47, s80
	s_cselect_b32 s87, s37, s86
	s_cselect_b32 s86, s43, s83
	v_lshl_add_u64 v[212:213], v[140:141], 0, s[48:49]
	s_mov_b64 s[88:89], 0xc000
	v_lshl_add_u64 v[214:215], v[212:213], 0, s[88:89]
	s_add_i32 m0, s57, 0xc000
	s_mov_b64 s[88:89], 0xe000
	ds_read_b128 v[174:177], v190
	ds_read_b128 v[178:181], v190 offset:1024
	ds_read_b128 v[182:185], v190 offset:2048
	ds_read_b128 v[192:195], v190 offset:3072
	ds_read_b128 v[196:199], v190 offset:4096
	ds_read_b128 v[200:203], v190 offset:5120
	ds_read_b128 v[204:207], v190 offset:6144
	ds_read_b128 v[208:211], v190 offset:7168
	global_load_lds_dwordx4 v[214:215], off
	v_lshl_add_u64 v[212:213], v[212:213], 0, s[88:89]
	s_add_i32 m0, s57, 0xe000
	s_nop 0
	global_load_lds_dwordx4 v[212:213], off
	s_waitcnt vmcnt(8)
	s_waitcnt lgkmcnt(0)
	s_barrier
	s_setprio 1
	s_waitcnt lgkmcnt(0)
	v_mfma_f32_16x16x32_bf16 v[124:127], v[142:145], v[174:177], v[124:127]
	v_mfma_f32_16x16x32_bf16 v[116:119], v[142:145], v[182:185], v[116:119]
	v_mfma_f32_16x16x32_bf16 v[108:111], v[142:145], v[196:199], v[108:111]
	v_mfma_f32_16x16x32_bf16 v[100:103], v[142:145], v[204:207], v[100:103]
	v_mfma_f32_16x16x32_bf16 v[120:123], v[150:153], v[174:177], v[120:123]
	v_mfma_f32_16x16x32_bf16 v[112:115], v[150:153], v[182:185], v[112:115]
	v_mfma_f32_16x16x32_bf16 v[104:107], v[150:153], v[196:199], v[104:107]
	v_mfma_f32_16x16x32_bf16 v[96:99], v[150:153], v[204:207], v[96:99]
	v_mfma_f32_16x16x32_bf16 v[124:127], v[146:149], v[178:181], v[124:127]
	v_mfma_f32_16x16x32_bf16 v[116:119], v[146:149], v[192:195], v[116:119]
	v_mfma_f32_16x16x32_bf16 v[108:111], v[146:149], v[200:203], v[108:111]
	v_mfma_f32_16x16x32_bf16 v[100:103], v[146:149], v[208:211], v[100:103]
	v_mfma_f32_16x16x32_bf16 v[120:123], v[154:157], v[178:181], v[120:123]
	v_mfma_f32_16x16x32_bf16 v[112:115], v[154:157], v[192:195], v[112:115]
	v_mfma_f32_16x16x32_bf16 v[104:107], v[154:157], v[200:203], v[104:107]
	v_mfma_f32_16x16x32_bf16 v[96:99], v[154:157], v[208:211], v[96:99]
	s_setprio 0
	s_setprio 1
	v_mfma_f32_16x16x32_bf16 v[60:63], v[158:161], v[174:177], v[60:63]
	v_mfma_f32_16x16x32_bf16 v[52:55], v[158:161], v[182:185], v[52:55]
	v_mfma_f32_16x16x32_bf16 v[44:47], v[158:161], v[196:199], v[44:47]
	v_mfma_f32_16x16x32_bf16 v[36:39], v[158:161], v[204:207], v[36:39]
	v_mfma_f32_16x16x32_bf16 v[56:59], v[166:169], v[174:177], v[56:59]
	v_mfma_f32_16x16x32_bf16 v[48:51], v[166:169], v[182:185], v[48:51]
	v_mfma_f32_16x16x32_bf16 v[40:43], v[166:169], v[196:199], v[40:43]
	v_mfma_f32_16x16x32_bf16 v[32:35], v[166:169], v[204:207], v[32:35]
	v_mfma_f32_16x16x32_bf16 v[60:63], v[162:165], v[178:181], v[60:63]
	v_mfma_f32_16x16x32_bf16 v[52:55], v[162:165], v[192:195], v[52:55]
	v_mfma_f32_16x16x32_bf16 v[44:47], v[162:165], v[200:203], v[44:47]
	v_mfma_f32_16x16x32_bf16 v[36:39], v[162:165], v[208:211], v[36:39]
	v_mfma_f32_16x16x32_bf16 v[56:59], v[170:173], v[178:181], v[56:59]
	v_mfma_f32_16x16x32_bf16 v[48:51], v[170:173], v[192:195], v[48:51]
	v_mfma_f32_16x16x32_bf16 v[40:43], v[170:173], v[200:203], v[40:43]
	v_mfma_f32_16x16x32_bf16 v[32:35], v[170:173], v[208:211], v[32:35]
	s_setprio 0
	s_barrier
	s_add_i32 s83, s94, s56
	v_lshl_add_u64 v[212:213], s[84:85], 0, v[130:131]
	s_mov_b32 m0, s83
	ds_read_b128 v[174:177], v190 offset:16384
	ds_read_b128 v[178:181], v190 offset:17408
	ds_read_b128 v[182:185], v190 offset:18432
	ds_read_b128 v[192:195], v190 offset:19456
	ds_read_b128 v[196:199], v190 offset:20480
	ds_read_b128 v[200:203], v190 offset:21504
	ds_read_b128 v[204:207], v190 offset:22528
	ds_read_b128 v[208:211], v190 offset:23552
	global_load_lds_dwordx4 v[212:213], off
	v_lshl_add_u64 v[214:215], v[212:213], 0, s[4:5]
	s_add_i32 m0, s83, 0x2000
	s_add_i32 s83, s95, s56
	global_load_lds_dwordx4 v[214:215], off
	v_lshl_add_u64 v[214:215], v[212:213], 0, s[6:7]
	s_mov_b32 m0, s83
	s_nop 0
	global_load_lds_dwordx4 v[214:215], off
	v_lshl_add_u64 v[214:215], v[212:213], 0, s[8:9]
	s_add_i32 m0, s83, 0x2000
	s_nop 0
	global_load_lds_dwordx4 v[214:215], off
	v_lshl_add_u64 v[214:215], s[86:87], 0, v[128:129]
	s_mov_b32 m0, s57
	v_lshl_add_u64 v[216:217], v[214:215], 0, s[10:11]
	global_load_lds_dwordx4 v[214:215], off
	s_mov_b32 m0, s58
	s_nop 0
	global_load_lds_dwordx4 v[216:217], off
	s_waitcnt vmcnt(8)
	s_waitcnt lgkmcnt(0)
	s_barrier
; #define PG8_STAGE(bufoff, gbase, voff) do { _Pragma("unroll") for (int _i = 0; _i < 2; ++_i) \
;         __builtin_amdgcn_global_load_lds((const unsigned*)((const char*)(gbase) + (size_t)_i * p##voff + (voff)), (LAS unsigned*)(lds + (bufoff) + ldsw + _i * 8192), 16, 0, 0); } while (0)
; #define PG8_LDA(dst, b, h) do { _Pragma("unroll") for (int m = 0; m < 4; ++m) _Pragma("unroll") for (int k = 0; k < 2; ++k) dst[m][k] = *(const LAS bf16x8*)(lds + PG8_SA(b, h) + aoff + m * 2048 + k * 1024); } while (0)
; #define PG8_LDB(dst, b, h) do { _Pragma("unroll") for (int n = 0; n < 2; ++n) _Pragma("unroll") for (int k = 0; k < 2; ++k) dst[n][k] = *(const LAS bf16x8*)(lds + PG8_SB(b, h) + boff + n * 2048 + k * 1024); } while (0)
; #define PG8_WAIT_V(n) asm volatile("s_waitcnt vmcnt(" #n ")" ::: "memory")
; #define PG8_WAIT_L(n) asm volatile("s_waitcnt lgkmcnt(" #n ")" ::: "memory")
; #define PG8_BAR __builtin_amdgcn_s_barrier()
; #define PG8_SCHED __builtin_amdgcn_sched_barrier(0)
;     ...
;             PG8_LDA(At, 0, 1); PG8_STAGE(PG8_SB(0, 0), b2, voffB); PG8_STAGE(PG8_SB(0, 1), b2 + hstepB, voffB); PG8_STAGE(PG8_SA(0, 0), a2, voffA);
;             PG8_WAIT_V(8); PG8_WAIT_L(0); PG8_BAR; PG8_MMA(1, 0, At, B0); PG8_MMA(1, 1, At, B1); PG8_BAR; PG8_SCHED;
;             PG8_LDB(B0, 1, 0); PG8_LDB(B1, 1, 1); PG8_SCHED; PG8_LDA(At, 1, 0); PG8_STAGE(PG8_SA(0, 1), a2 + hstepA, voffA);
;             PG8_WAIT_V(8); PG8_WAIT_L(0); PG8_BAR; PG8_MMA(0, 0, At, B0); PG8_MMA(0, 1, At, B1); PG8_BAR; PG8_SCHED;
;             PG8_LDA(At, 1, 1); PG8_STAGE(PG8_SB(1, 0), b3, voffB); PG8_STAGE(PG8_SB(1, 1), b3 + hstepB, voffB); PG8_STAGE(PG8_SA(1, 0), a3, voffA);
	s_setprio 1
	s_waitcnt lgkmcnt(0)
	v_mfma_f32_16x16x32_bf16 v[92:95], v[142:145], v[174:177], v[92:95]
	v_mfma_f32_16x16x32_bf16 v[84:87], v[142:145], v[182:185], v[84:87]
	v_mfma_f32_16x16x32_bf16 v[76:79], v[142:145], v[196:199], v[76:79]
	v_mfma_f32_16x16x32_bf16 v[68:71], v[142:145], v[204:207], v[68:71]
	v_mfma_f32_16x16x32_bf16 v[88:91], v[150:153], v[174:177], v[88:91]
	v_mfma_f32_16x16x32_bf16 v[80:83], v[150:153], v[182:185], v[80:83]
	v_mfma_f32_16x16x32_bf16 v[72:75], v[150:153], v[196:199], v[72:75]
	v_mfma_f32_16x16x32_bf16 v[64:67], v[150:153], v[204:207], v[64:67]
	v_mfma_f32_16x16x32_bf16 v[92:95], v[146:149], v[178:181], v[92:95]
	v_mfma_f32_16x16x32_bf16 v[84:87], v[146:149], v[192:195], v[84:87]
	v_mfma_f32_16x16x32_bf16 v[76:79], v[146:149], v[200:203], v[76:79]
	v_mfma_f32_16x16x32_bf16 v[68:71], v[146:149], v[208:211], v[68:71]
	v_mfma_f32_16x16x32_bf16 v[88:91], v[154:157], v[178:181], v[88:91]
	v_mfma_f32_16x16x32_bf16 v[80:83], v[154:157], v[192:195], v[80:83]
	v_mfma_f32_16x16x32_bf16 v[72:75], v[154:157], v[200:203], v[72:75]
	v_mfma_f32_16x16x32_bf16 v[64:67], v[154:157], v[208:211], v[64:67]
	s_setprio 0
	s_setprio 1
	v_mfma_f32_16x16x32_bf16 v[28:31], v[158:161], v[174:177], v[28:31]
	v_mfma_f32_16x16x32_bf16 v[20:23], v[158:161], v[182:185], v[20:23]
	v_mfma_f32_16x16x32_bf16 v[12:15], v[158:161], v[196:199], v[12:15]
	v_mfma_f32_16x16x32_bf16 v[4:7], v[158:161], v[204:207], v[4:7]
	v_mfma_f32_16x16x32_bf16 v[24:27], v[166:169], v[174:177], v[24:27]
	v_mfma_f32_16x16x32_bf16 v[16:19], v[166:169], v[182:185], v[16:19]
	v_mfma_f32_16x16x32_bf16 v[8:11], v[166:169], v[196:199], v[8:11]
	v_mfma_f32_16x16x32_bf16 v[0:3], v[166:169], v[204:207], v[0:3]
	v_mfma_f32_16x16x32_bf16 v[28:31], v[162:165], v[178:181], v[28:31]
	v_mfma_f32_16x16x32_bf16 v[20:23], v[162:165], v[192:195], v[20:23]
	v_mfma_f32_16x16x32_bf16 v[12:15], v[162:165], v[200:203], v[12:15]
	v_mfma_f32_16x16x32_bf16 v[4:7], v[162:165], v[208:211], v[4:7]
	v_mfma_f32_16x16x32_bf16 v[24:27], v[170:173], v[178:181], v[24:27]
	v_mfma_f32_16x16x32_bf16 v[16:19], v[170:173], v[192:195], v[16:19]
	v_mfma_f32_16x16x32_bf16 v[8:11], v[170:173], v[200:203], v[8:11]
	v_mfma_f32_16x16x32_bf16 v[0:3], v[170:173], v[208:211], v[0:3]
	s_setprio 0
	s_barrier
	s_add_i32 s83, 0, 0x18000
	v_add_u32_e32 v132, s83, v187
	s_add_i32 s84, 0, 0x1c000
	ds_read_b128 v[142:145], v132
	ds_read_b128 v[146:149], v132 offset:1024
	ds_read_b128 v[150:153], v132 offset:2048
	ds_read_b128 v[154:157], v132 offset:3072
	v_add_u32_e32 v132, s84, v187
	ds_read_b128 v[158:161], v132
	ds_read_b128 v[162:165], v132 offset:1024
	ds_read_b128 v[166:169], v132 offset:2048
	ds_read_b128 v[170:173], v132 offset:3072
	s_mov_b32 m0, s59
	v_lshl_add_u64 v[216:217], v[214:215], 0, s[12:13]
	ds_read_b128 v[174:177], v190 offset:32768
	ds_read_b128 v[178:181], v190 offset:33792
	ds_read_b128 v[182:185], v190 offset:34816
	ds_read_b128 v[192:195], v190 offset:35840
	ds_read_b128 v[196:199], v190 offset:36864
	ds_read_b128 v[200:203], v190 offset:37888
	ds_read_b128 v[204:207], v190 offset:38912
	ds_read_b128 v[208:211], v190 offset:39936
	global_load_lds_dwordx4 v[216:217], off
	v_lshl_add_u64 v[214:215], v[214:215], 0, s[14:15]
	s_mov_b32 m0, s60
	s_nop 0
	global_load_lds_dwordx4 v[214:215], off
	s_waitcnt vmcnt(8)
	s_waitcnt lgkmcnt(0)
	s_barrier
	s_setprio 1
	s_waitcnt lgkmcnt(0)
	v_mfma_f32_16x16x32_bf16 v[124:127], v[142:145], v[174:177], v[124:127]
	v_mfma_f32_16x16x32_bf16 v[116:119], v[142:145], v[182:185], v[116:119]
	v_mfma_f32_16x16x32_bf16 v[108:111], v[142:145], v[196:199], v[108:111]
	v_mfma_f32_16x16x32_bf16 v[100:103], v[142:145], v[204:207], v[100:103]
	v_mfma_f32_16x16x32_bf16 v[120:123], v[150:153], v[174:177], v[120:123]
	v_mfma_f32_16x16x32_bf16 v[112:115], v[150:153], v[182:185], v[112:115]
	v_mfma_f32_16x16x32_bf16 v[104:107], v[150:153], v[196:199], v[104:107]
	v_mfma_f32_16x16x32_bf16 v[96:99], v[150:153], v[204:207], v[96:99]
	v_mfma_f32_16x16x32_bf16 v[124:127], v[146:149], v[178:181], v[124:127]
	v_mfma_f32_16x16x32_bf16 v[116:119], v[146:149], v[192:195], v[116:119]
	v_mfma_f32_16x16x32_bf16 v[108:111], v[146:149], v[200:203], v[108:111]
	v_mfma_f32_16x16x32_bf16 v[100:103], v[146:149], v[208:211], v[100:103]
	v_mfma_f32_16x16x32_bf16 v[120:123], v[154:157], v[178:181], v[120:123]
	v_mfma_f32_16x16x32_bf16 v[112:115], v[154:157], v[192:195], v[112:115]
	v_mfma_f32_16x16x32_bf16 v[104:107], v[154:157], v[200:203], v[104:107]
	v_mfma_f32_16x16x32_bf16 v[96:99], v[154:157], v[208:211], v[96:99]
	s_setprio 0
	s_setprio 1
	v_mfma_f32_16x16x32_bf16 v[60:63], v[158:161], v[174:177], v[60:63]
	v_mfma_f32_16x16x32_bf16 v[52:55], v[158:161], v[182:185], v[52:55]
	v_mfma_f32_16x16x32_bf16 v[44:47], v[158:161], v[196:199], v[44:47]
	v_mfma_f32_16x16x32_bf16 v[36:39], v[158:161], v[204:207], v[36:39]
	v_mfma_f32_16x16x32_bf16 v[56:59], v[166:169], v[174:177], v[56:59]
	v_mfma_f32_16x16x32_bf16 v[48:51], v[166:169], v[182:185], v[48:51]
	v_mfma_f32_16x16x32_bf16 v[40:43], v[166:169], v[196:199], v[40:43]
	v_mfma_f32_16x16x32_bf16 v[32:35], v[166:169], v[204:207], v[32:35]
	v_mfma_f32_16x16x32_bf16 v[60:63], v[162:165], v[178:181], v[60:63]
	v_mfma_f32_16x16x32_bf16 v[52:55], v[162:165], v[192:195], v[52:55]
	v_mfma_f32_16x16x32_bf16 v[44:47], v[162:165], v[200:203], v[44:47]
	v_mfma_f32_16x16x32_bf16 v[36:39], v[162:165], v[208:211], v[36:39]
	v_mfma_f32_16x16x32_bf16 v[56:59], v[170:173], v[178:181], v[56:59]
	v_mfma_f32_16x16x32_bf16 v[48:51], v[170:173], v[192:195], v[48:51]
	v_mfma_f32_16x16x32_bf16 v[40:43], v[170:173], v[200:203], v[40:43]
	v_mfma_f32_16x16x32_bf16 v[32:35], v[170:173], v[208:211], v[32:35]
	s_setprio 0
	s_barrier
; #define PG8_STAGE(bufoff, gbase, voff) do { _Pragma("unroll") for (int _i = 0; _i < 2; ++_i) \
;         __builtin_amdgcn_global_load_lds((const unsigned*)((const char*)(gbase) + (size_t)_i * p##voff + (voff)), (LAS unsigned*)(lds + (bufoff) + ldsw + _i * 8192), 16, 0, 0); } while (0)
; #define PG8_LDA(dst, b, h) do { _Pragma("unroll") for (int m = 0; m < 4; ++m) _Pragma("unroll") for (int k = 0; k < 2; ++k) dst[m][k] = *(const LAS bf16x8*)(lds + PG8_SA(b, h) + aoff + m * 2048 + k * 1024); } while (0)
; #define PG8_WAIT_V(n) asm volatile("s_waitcnt vmcnt(" #n ")" ::: "memory")
; #define PG8_WAIT_L(n) asm volatile("s_waitcnt lgkmcnt(" #n ")" ::: "memory")
; #define PG8_BAR __builtin_amdgcn_s_barrier()
; #define PG8_SCHED __builtin_amdgcn_sched_barrier(0)
;     ...
;             PG8_LDA(At, 1, 1); PG8_STAGE(PG8_SB(1, 0), b3, voffB); PG8_STAGE(PG8_SB(1, 1), b3 + hstepB, voffB); PG8_STAGE(PG8_SA(1, 0), a3, voffA);
;             PG8_WAIT_V(8); PG8_WAIT_L(0); PG8_BAR; PG8_MMA(1, 0, At, B0); PG8_MMA(1, 1, At, B1); PG8_BAR; PG8_SCHED;
;         }
;     __device__ __forceinline__ void operator()(const Acc& acc, const Unit& u, int wr, int wc, int fr, int fq) const {
;         { const int ln = (int)__builtin_amdgcn_mbcnt_hi(~0u, __builtin_amdgcn_mbcnt_lo(~0u, 0u)); fr = ln & 15; fq = ln >> 4; }
;         const int rowb = u.pm * 256 + wr * 64 + fr, col0 = u.pn * 256 + wc * 32 + 8 * fq; const int b = (u.pm * 256) / S;
;         const size_t yb = (((size_t)u.pm * 16 + u.pn) * 256 + (wr * 64 + fr)) * 256 + wc * 32 + 8 * fq;
; #pragma unroll
;         for (int bj = 0; bj < 2; ++bj) {
;             f32x4 gm[2], G[2], Bc[2];
; #pragma unroll
;             for (int n = 0; n < 2; ++n) { const int c = col0 + bj * 128 + n * 4; gm[n] = *(const f32x4*)(gate + (size_t)b * NADA + c) + 1.0f; G[n] = *(const f32x4*)(lg + c) * ALPHA; Bc[n] = *(const f32x4*)(lb + c) * ALPHA; }
; #pragma unroll
;             for (int hf = 0; hf < 2; ++hf) {
;                 u32x4 yv[4]; f32x2 st[4];
; #pragma unroll
;                 for (int m = 0; m < 4; ++m) { const int row = rowb + hf * 128 + m * 16; yv[m] = *(const u32x4*)(y1 + yb + (size_t)(hf * 128 + m * 16) * 256 + bj * 128); st[m] = *(const f32x2*)(stats + (size_t)row * 2); }
	s_add_i32 s83, s83, s56
	v_lshl_add_u64 v[214:215], v[212:213], 0, s[20:21]
	s_mov_b32 m0, s83
	ds_read_b128 v[174:177], v190 offset:49152
	ds_read_b128 v[178:181], v190 offset:50176
	ds_read_b128 v[182:185], v190 offset:51200
	ds_read_b128 v[192:195], v190 offset:52224
	ds_read_b128 v[196:199], v190 offset:53248
	ds_read_b128 v[200:203], v190 offset:54272
	ds_read_b128 v[204:207], v190 offset:55296
	ds_read_b128 v[208:211], v190 offset:56320
	global_load_lds_dwordx4 v[214:215], off
	v_lshl_add_u64 v[214:215], v[212:213], 0, s[22:23]
	s_add_i32 m0, s83, 0x2000
	s_add_i32 s83, s84, s56
	global_load_lds_dwordx4 v[214:215], off
	v_lshl_add_u64 v[214:215], v[212:213], 0, s[24:25]
	s_mov_b32 m0, s83
	v_lshl_add_u64 v[212:213], v[212:213], 0, s[26:27]
	global_load_lds_dwordx4 v[214:215], off
	s_add_i32 m0, s83, 0x2000
	s_nop 0
	global_load_lds_dwordx4 v[212:213], off
	v_lshl_add_u64 v[212:213], s[50:51], 0, v[128:129]
	s_mov_b32 m0, s71
	s_nop 0
	global_load_lds_dwordx4 v[212:213], off
	v_lshl_add_u64 v[212:213], v[212:213], 0, s[10:11]
	s_mov_b32 m0, s72
	s_nop 0
	global_load_lds_dwordx4 v[212:213], off
	s_waitcnt vmcnt(8)
	s_waitcnt lgkmcnt(0)
	s_barrier
	s_setprio 1
	s_waitcnt lgkmcnt(0)
	v_mfma_f32_16x16x32_bf16 v[92:95], v[142:145], v[174:177], v[92:95]
	v_mfma_f32_16x16x32_bf16 v[84:87], v[142:145], v[182:185], v[84:87]
	v_mfma_f32_16x16x32_bf16 v[76:79], v[142:145], v[196:199], v[76:79]
	v_mfma_f32_16x16x32_bf16 v[68:71], v[142:145], v[204:207], v[68:71]
	v_mfma_f32_16x16x32_bf16 v[88:91], v[150:153], v[174:177], v[88:91]
	v_mfma_f32_16x16x32_bf16 v[80:83], v[150:153], v[182:185], v[80:83]
	v_mfma_f32_16x16x32_bf16 v[72:75], v[150:153], v[196:199], v[72:75]
	v_mfma_f32_16x16x32_bf16 v[64:67], v[150:153], v[204:207], v[64:67]
	v_mfma_f32_16x16x32_bf16 v[92:95], v[146:149], v[178:181], v[92:95]
	v_mfma_f32_16x16x32_bf16 v[84:87], v[146:149], v[192:195], v[84:87]
	v_mfma_f32_16x16x32_bf16 v[76:79], v[146:149], v[200:203], v[76:79]
	v_mfma_f32_16x16x32_bf16 v[68:71], v[146:149], v[208:211], v[68:71]
	v_mfma_f32_16x16x32_bf16 v[88:91], v[154:157], v[178:181], v[88:91]
	v_mfma_f32_16x16x32_bf16 v[80:83], v[154:157], v[192:195], v[80:83]
	v_mfma_f32_16x16x32_bf16 v[72:75], v[154:157], v[200:203], v[72:75]
	v_mfma_f32_16x16x32_bf16 v[64:67], v[154:157], v[208:211], v[64:67]
	s_setprio 0
	s_setprio 1
	v_mfma_f32_16x16x32_bf16 v[28:31], v[158:161], v[174:177], v[28:31]
	v_mfma_f32_16x16x32_bf16 v[20:23], v[158:161], v[182:185], v[20:23]
	v_mfma_f32_16x16x32_bf16 v[12:15], v[158:161], v[196:199], v[12:15]
	v_mfma_f32_16x16x32_bf16 v[4:7], v[158:161], v[204:207], v[4:7]
	v_mfma_f32_16x16x32_bf16 v[24:27], v[166:169], v[174:177], v[24:27]
	v_mfma_f32_16x16x32_bf16 v[16:19], v[166:169], v[182:185], v[16:19]
	v_mfma_f32_16x16x32_bf16 v[8:11], v[166:169], v[196:199], v[8:11]
	v_mfma_f32_16x16x32_bf16 v[0:3], v[166:169], v[204:207], v[0:3]
	v_mfma_f32_16x16x32_bf16 v[28:31], v[162:165], v[178:181], v[28:31]
	v_mfma_f32_16x16x32_bf16 v[20:23], v[162:165], v[192:195], v[20:23]
	v_mfma_f32_16x16x32_bf16 v[12:15], v[162:165], v[200:203], v[12:15]
	v_mfma_f32_16x16x32_bf16 v[4:7], v[162:165], v[208:211], v[4:7]
	v_mfma_f32_16x16x32_bf16 v[24:27], v[170:173], v[178:181], v[24:27]
	v_mfma_f32_16x16x32_bf16 v[16:19], v[170:173], v[192:195], v[16:19]
	v_mfma_f32_16x16x32_bf16 v[8:11], v[170:173], v[200:203], v[8:11]
	v_mfma_f32_16x16x32_bf16 v[0:3], v[170:173], v[208:211], v[0:3]
	s_setprio 0
	s_barrier
	s_add_i32 s82, s82, 2
	s_add_u32 s80, s80, 0x100
	s_addc_u32 s81, s81, 0
	s_add_u32 s48, s48, 0x10000
	s_addc_u32 s49, s49, 0
	s_cmpk_gt_u32 s82, 0xfd
	s_cbranch_scc0 .LBB0_1281
	s_lshl_b32 s37, s46, 8
	v_lshrrev_b32_e32 v132, 1, v191
	s_or_b32 s37, s37, s74
	v_and_b32_e32 v141, 56, v132
	s_ashr_i32 s43, s42, 31
	v_add_u32_e32 v140, s37, v141
	s_lshr_b32 s37, s43, 28
	s_lshl_b32 s35, s42, 8
	s_add_i32 s37, s42, s37
	s_ashr_i32 s47, s46, 31
	s_add_i32 s35, s35, s73
	s_ashr_i32 s37, s37, 4
	s_lshl_b64 s[42:43], s[42:43], 12
	s_lshl_b64 s[44:45], s[46:47], 8
	v_and_b32_e32 v150, 15, v191
	s_add_u32 s42, s42, s44
	s_addc_u32 s43, s43, s45
	v_or_b32_e32 v132, s73, v150
	v_lshl_add_u64 v[148:149], s[42:43], 0, v[132:133]
	s_mul_hi_i32 s43, s37, 0x18000
	s_mul_i32 s37, s37, 0x18000
	v_add_u32_e32 v132, s74, v141
	v_ashrrev_i32_e32 v141, 31, v140
	v_readlane_b32 s76, v245, 10
	s_add_u32 s42, s69, s37
	v_lshlrev_b64 v[220:221], 9, v[148:149]
	v_or_b32_e32 v154, s35, v150
	v_lshlrev_b64 v[140:141], 2, v[140:141]
	v_readlane_b32 s78, v245, 12
	v_readlane_b32 s79, v245, 13
	v_readlane_b32 s80, v245, 14
	v_readlane_b32 s81, v245, 15
	s_addc_u32 s43, s70, s43
	v_lshl_or_b32 v220, v132, 1, v220
	v_ashrrev_i32_e32 v155, 31, v154
	v_lshl_add_u64 v[142:143], s[78:79], 0, v[140:141]
	v_lshl_add_u64 v[144:145], s[80:81], 0, v[140:141]
	v_lshl_add_u64 v[146:147], s[42:43], 0, v[140:141]
	v_lshl_add_u64 v[148:149], s[16:17], 0, v[220:221]
	v_lshl_add_u64 v[140:141], v[154:155], 3, s[18:19]
	global_load_dwordx4 v[164:167], v[142:143], off offset:16
	global_load_dwordx4 v[168:171], v[142:143], off
	global_load_dwordx4 v[182:185], v[144:145], off offset:16
	global_load_dwordx4 v[192:195], v[144:145], off
	global_load_dwordx4 v[196:199], v[146:147], off offset:16
	global_load_dwordx4 v[200:203], v[146:147], off
	global_load_dwordx4 v[204:207], v[148:149], off
	global_load_dwordx2 v[222:223], v[140:141], off
	v_or_b32_e32 v152, 16, v154
	v_add_co_u32_e32 v150, vcc, s66, v148
	v_ashrrev_i32_e32 v153, 31, v152
	s_nop 0
	v_addc_co_u32_e32 v151, vcc, 0, v149, vcc
	v_lshl_add_u64 v[152:153], v[152:153], 3, s[18:19]
	global_load_dwordx4 v[208:211], v[150:151], off
	global_load_dwordx2 v[224:225], v[152:153], off
	v_add_co_u32_e32 v158, vcc, s67, v148
	v_or_b32_e32 v156, 32, v154
	s_nop 0
	v_addc_co_u32_e32 v159, vcc, 0, v149, vcc
	v_or_b32_e32 v154, 48, v154
	v_ashrrev_i32_e32 v157, 31, v156
	global_load_dwordx4 v[212:215], v[158:159], off
	v_ashrrev_i32_e32 v155, 31, v154
	v_lshl_add_u64 v[160:161], v[156:157], 3, s[18:19]
	v_add_co_u32_e32 v156, vcc, s68, v148
	v_lshl_add_u64 v[154:155], v[154:155], 3, s[18:19]
	s_nop 0
	v_addc_co_u32_e32 v157, vcc, 0, v149, vcc
	global_load_dwordx2 v[226:227], v[160:161], off
	global_load_dwordx4 v[216:219], v[156:157], off
	global_load_dwordx2 v[228:229], v[154:155], off
	v_readlane_b32 s42, v245, 61
	v_readlane_b32 s43, v245, 62
	s_mov_b32 s46, s34
	s_mov_b64 s[48:49], s[40:41]
	s_mov_b64 s[44:45], s[38:39]
	v_readlane_b32 s77, v245, 11
	v_readlane_b32 s82, v245, 16
	v_readlane_b32 s83, v245, 17
	v_readlane_b32 s84, v245, 18
	v_readlane_b32 s85, v245, 19
	v_readlane_b32 s86, v245, 20
	v_readlane_b32 s87, v245, 21
	v_readlane_b32 s88, v245, 22
	v_readlane_b32 s89, v245, 23
	v_readlane_b32 s90, v245, 24
	v_readlane_b32 s91, v245, 25
	s_waitcnt vmcnt(0)
; __device__ __forceinline__ u32x4 pack8f(f32x4 lo, f32x4 hi) { u32x4 w; w.x = cvtpk(lo[0], lo[1]); w.y = cvtpk(lo[2], lo[3]); w.z = cvtpk(hi[0], hi[1]); w.w = cvtpk(hi[2], hi[3]); return w; }
;     __device__ __forceinline__ void operator()(const Acc& acc, const Unit& u, int wr, int wc, int fr, int fq) const {
;     ...
; #pragma unroll
;         for (int bj = 0; bj < 2; ++bj) {
;             f32x4 gm[2], G[2], Bc[2];
; #pragma unroll
;             for (int n = 0; n < 2; ++n) { const int c = col0 + bj * 128 + n * 4; gm[n] = *(const f32x4*)(gate + (size_t)b * NADA + c) + 1.0f; G[n] = *(const f32x4*)(lg + c) * ALPHA; Bc[n] = *(const f32x4*)(lb + c) * ALPHA; }
; #pragma unroll
;             for (int hf = 0; hf < 2; ++hf) {
;                 u32x4 yv[4]; f32x2 st[4];
; #pragma unroll
;                 for (int m = 0; m < 4; ++m) { const int row = rowb + hf * 128 + m * 16; yv[m] = *(const u32x4*)(y1 + yb + (size_t)(hf * 128 + m * 16) * 256 + bj * 128); st[m] = *(const f32x2*)(stats + (size_t)row * 2); }
; #pragma unroll
;                 for (int m = 0; m < 4; ++m) { const int row = rowb + hf * 128 + m * 16;
;                     f32x4 lo, hi; unpack8(yv[m], lo, hi); const float r = st[m][1], mr = st[m][0] * r;
;                     lo = (lo * r - mr) * G[0] + Bc[0] + gm[0] * acc[hf][bj][m][0]; hi = (hi * r - mr) * G[1] + Bc[1] + gm[1] * acc[hf][bj][m][1];
;                     *(u32x4*)(y2 + yb + (size_t)(hf * 128 + m * 16) * 256 + bj * 128) = pack8f(lo, hi); }
	v_pk_mul_f32 v[162:163], v[166:167], s[28:29] op_sel_hi:[1,0]
	v_pk_mul_f32 v[166:167], v[184:185], s[28:29] op_sel_hi:[1,0]
	v_pk_mul_f32 v[178:179], v[194:195], s[28:29] op_sel_hi:[1,0]
	v_pk_mul_f32 v[180:181], v[192:193], s[28:29] op_sel_hi:[1,0]
	v_pk_add_f32 v[184:185], v[200:201], 1.0 op_sel_hi:[1,0]
	v_lshlrev_b32_e32 v192, 16, v204
	v_and_b32_e32 v193, 0xffff0000, v204
	v_lshlrev_b32_e32 v194, 16, v205
	v_and_b32_e32 v195, 0xffff0000, v205
	v_pk_mul_f32 v[200:201], v[222:223], v[222:223] op_sel:[0,1] op_sel_hi:[1,0]
	v_pk_mul_f32 v[174:175], v[170:171], s[28:29] op_sel_hi:[1,0]
	v_pk_mul_f32 v[176:177], v[168:169], s[28:29] op_sel_hi:[1,0]
	v_pk_fma_f32 v[192:193], v[222:223], v[192:193], v[200:201] op_sel:[1,0,0] op_sel_hi:[1,1,0] neg_lo:[0,0,1] neg_hi:[0,0,1]
	v_pk_fma_f32 v[194:195], v[222:223], v[194:195], v[200:201] op_sel:[1,0,0] op_sel_hi:[1,1,0] neg_lo:[0,0,1] neg_hi:[0,0,1]
	v_pk_mul_f32 v[172:173], v[182:183], s[28:29] op_sel_hi:[1,0]
	v_pk_add_f32 v[182:183], v[202:203], 1.0 op_sel_hi:[1,0]
	v_pk_add_f32 v[168:169], v[198:199], 1.0 op_sel_hi:[1,0]
	v_pk_add_f32 v[170:171], v[196:197], 1.0 op_sel_hi:[1,0]
	v_lshlrev_b32_e32 v196, 16, v206
	v_and_b32_e32 v197, 0xffff0000, v206
	v_lshlrev_b32_e32 v198, 16, v207
	v_and_b32_e32 v199, 0xffff0000, v207
	v_pk_fma_f32 v[194:195], v[174:175], v[194:195], v[178:179]
	v_pk_fma_f32 v[192:193], v[176:177], v[192:193], v[180:181]
	v_pk_mul_f32 v[164:165], v[164:165], s[28:29] op_sel_hi:[1,0]
	v_pk_fma_f32 v[126:127], v[126:127], v[182:183], v[194:195]
	v_pk_fma_f32 v[124:125], v[124:125], v[184:185], v[192:193]
	v_pk_fma_f32 v[192:193], v[222:223], v[196:197], v[200:201] op_sel:[1,0,0] op_sel_hi:[1,1,0] neg_lo:[0,0,1] neg_hi:[0,0,1]
	v_pk_fma_f32 v[194:195], v[222:223], v[198:199], v[200:201] op_sel:[1,0,0] op_sel_hi:[1,1,0] neg_lo:[0,0,1] neg_hi:[0,0,1]
	v_pk_fma_f32 v[192:193], v[164:165], v[192:193], v[172:173]
	v_pk_fma_f32 v[194:195], v[162:163], v[194:195], v[166:167]
	v_pk_fma_f32 v[120:121], v[120:121], v[170:171], v[192:193]
	v_pk_fma_f32 v[194:195], v[122:123], v[168:169], v[194:195]
	v_cvt_pk_bf16_f32 v122, v124, v125
	v_cvt_pk_bf16_f32 v123, v126, v127
	v_cvt_pk_bf16_f32 v124, v120, v121
	v_cvt_pk_bf16_f32 v125, v194, v195
	v_lshl_add_u64 v[120:121], s[42:43], 0, v[220:221]
	global_store_dwordx4 v[120:121], v[122:125], off
	v_pk_mul_f32 v[194:195], v[224:225], v[224:225] op_sel:[0,1] op_sel_hi:[1,0]
	v_lshlrev_b32_e32 v126, 16, v210
	v_lshlrev_b32_e32 v124, 16, v209
	v_and_b32_e32 v125, 0xffff0000, v209
	v_lshlrev_b32_e32 v122, 16, v208
	v_and_b32_e32 v123, 0xffff0000, v208
	v_pk_fma_f32 v[124:125], v[224:225], v[124:125], v[194:195] op_sel:[1,0,0] op_sel_hi:[1,1,0] neg_lo:[0,0,1] neg_hi:[0,0,1]
	v_and_b32_e32 v127, 0xffff0000, v210
	v_pk_fma_f32 v[122:123], v[224:225], v[122:123], v[194:195] op_sel:[1,0,0] op_sel_hi:[1,1,0] neg_lo:[0,0,1] neg_hi:[0,0,1]
	v_pk_fma_f32 v[124:125], v[174:175], v[124:125], v[178:179]
	v_lshlrev_b32_e32 v192, 16, v211
	v_and_b32_e32 v193, 0xffff0000, v211
	v_pk_fma_f32 v[122:123], v[176:177], v[122:123], v[180:181]
	v_pk_fma_f32 v[118:119], v[118:119], v[182:183], v[124:125]
	v_pk_fma_f32 v[124:125], v[224:225], v[126:127], v[194:195] op_sel:[1,0,0] op_sel_hi:[1,1,0] neg_lo:[0,0,1] neg_hi:[0,0,1]
	v_pk_fma_f32 v[116:117], v[116:117], v[184:185], v[122:123]
	v_pk_fma_f32 v[122:123], v[224:225], v[192:193], v[194:195] op_sel:[1,0,0] op_sel_hi:[1,1,0] neg_lo:[0,0,1] neg_hi:[0,0,1]
	v_pk_fma_f32 v[124:125], v[164:165], v[124:125], v[172:173]
	v_pk_fma_f32 v[122:123], v[162:163], v[122:123], v[166:167]
	v_pk_fma_f32 v[112:113], v[112:113], v[170:171], v[124:125]
	v_pk_fma_f32 v[122:123], v[114:115], v[168:169], v[122:123]
	v_cvt_pk_bf16_f32 v114, v116, v117
	v_cvt_pk_bf16_f32 v116, v112, v113
	v_add_co_u32_e32 v112, vcc, s66, v120
	v_cvt_pk_bf16_f32 v115, v118, v119
	v_cvt_pk_bf16_f32 v117, v122, v123
	v_addc_co_u32_e32 v113, vcc, 0, v121, vcc
	global_store_dwordx4 v[112:113], v[114:117], off
	v_pk_mul_f32 v[124:125], v[226:227], v[226:227] op_sel:[0,1] op_sel_hi:[1,0]
	v_lshlrev_b32_e32 v118, 16, v214
	v_lshlrev_b32_e32 v116, 16, v213
	v_and_b32_e32 v117, 0xffff0000, v213
	v_lshlrev_b32_e32 v114, 16, v212
	v_and_b32_e32 v115, 0xffff0000, v212
	v_pk_fma_f32 v[116:117], v[226:227], v[116:117], v[124:125] op_sel:[1,0,0] op_sel_hi:[1,1,0] neg_lo:[0,0,1] neg_hi:[0,0,1]
	v_and_b32_e32 v119, 0xffff0000, v214
	v_pk_fma_f32 v[114:115], v[226:227], v[114:115], v[124:125] op_sel:[1,0,0] op_sel_hi:[1,1,0] neg_lo:[0,0,1] neg_hi:[0,0,1]
	v_pk_fma_f32 v[116:117], v[174:175], v[116:117], v[178:179]
	v_lshlrev_b32_e32 v122, 16, v215
	v_and_b32_e32 v123, 0xffff0000, v215
	v_pk_fma_f32 v[114:115], v[176:177], v[114:115], v[180:181]
	v_pk_fma_f32 v[110:111], v[110:111], v[182:183], v[116:117]
	v_pk_fma_f32 v[116:117], v[226:227], v[118:119], v[124:125] op_sel:[1,0,0] op_sel_hi:[1,1,0] neg_lo:[0,0,1] neg_hi:[0,0,1]
	v_pk_fma_f32 v[108:109], v[108:109], v[184:185], v[114:115]
	v_pk_fma_f32 v[114:115], v[226:227], v[122:123], v[124:125] op_sel:[1,0,0] op_sel_hi:[1,1,0] neg_lo:[0,0,1] neg_hi:[0,0,1]
	v_pk_fma_f32 v[116:117], v[164:165], v[116:117], v[172:173]
	v_pk_fma_f32 v[114:115], v[162:163], v[114:115], v[166:167]
	v_pk_fma_f32 v[104:105], v[104:105], v[170:171], v[116:117]
	v_pk_fma_f32 v[114:115], v[106:107], v[168:169], v[114:115]
	v_cvt_pk_bf16_f32 v106, v108, v109
	v_cvt_pk_bf16_f32 v108, v104, v105
	v_add_co_u32_e32 v104, vcc, s67, v120
	v_cvt_pk_bf16_f32 v107, v110, v111
	v_cvt_pk_bf16_f32 v109, v114, v115
	v_addc_co_u32_e32 v105, vcc, 0, v121, vcc
	global_store_dwordx4 v[104:105], v[106:109], off
	v_pk_mul_f32 v[116:117], v[228:229], v[228:229] op_sel:[0,1] op_sel_hi:[1,0]
; __device__ __forceinline__ u32x4 pack8f(f32x4 lo, f32x4 hi) { u32x4 w; w.x = cvtpk(lo[0], lo[1]); w.y = cvtpk(lo[2], lo[3]); w.z = cvtpk(hi[0], hi[1]); w.w = cvtpk(hi[2], hi[3]); return w; }
;     __device__ __forceinline__ void operator()(const Acc& acc, const Unit& u, int wr, int wc, int fr, int fq) const {
;     ...
;             for (int n = 0; n < 2; ++n) { const int c = col0 + bj * 128 + n * 4; gm[n] = *(const f32x4*)(gate + (size_t)b * NADA + c) + 1.0f; G[n] = *(const f32x4*)(lg + c) * ALPHA; Bc[n] = *(const f32x4*)(lb + c) * ALPHA; }
; #pragma unroll
;             for (int hf = 0; hf < 2; ++hf) {
;                 u32x4 yv[4]; f32x2 st[4];
; #pragma unroll
;                 for (int m = 0; m < 4; ++m) { const int row = rowb + hf * 128 + m * 16; yv[m] = *(const u32x4*)(y1 + yb + (size_t)(hf * 128 + m * 16) * 256 + bj * 128); st[m] = *(const f32x2*)(stats + (size_t)row * 2); }
; #pragma unroll
;                 for (int m = 0; m < 4; ++m) { const int row = rowb + hf * 128 + m * 16;
;                     f32x4 lo, hi; unpack8(yv[m], lo, hi); const float r = st[m][1], mr = st[m][0] * r;
;                     lo = (lo * r - mr) * G[0] + Bc[0] + gm[0] * acc[hf][bj][m][0]; hi = (hi * r - mr) * G[1] + Bc[1] + gm[1] * acc[hf][bj][m][1];
;                     *(u32x4*)(y2 + yb + (size_t)(hf * 128 + m * 16) * 256 + bj * 128) = pack8f(lo, hi); }
;                 asm volatile("" ::: "memory");
;             }
	v_lshlrev_b32_e32 v110, 16, v218
	v_lshlrev_b32_e32 v108, 16, v217
	v_and_b32_e32 v109, 0xffff0000, v217
	v_lshlrev_b32_e32 v106, 16, v216
	v_and_b32_e32 v107, 0xffff0000, v216
	v_pk_fma_f32 v[108:109], v[228:229], v[108:109], v[116:117] op_sel:[1,0,0] op_sel_hi:[1,1,0] neg_lo:[0,0,1] neg_hi:[0,0,1]
	v_and_b32_e32 v111, 0xffff0000, v218
	v_pk_fma_f32 v[106:107], v[228:229], v[106:107], v[116:117] op_sel:[1,0,0] op_sel_hi:[1,1,0] neg_lo:[0,0,1] neg_hi:[0,0,1]
	v_pk_fma_f32 v[108:109], v[174:175], v[108:109], v[178:179]
	v_lshlrev_b32_e32 v114, 16, v219
	v_and_b32_e32 v115, 0xffff0000, v219
	v_pk_fma_f32 v[106:107], v[176:177], v[106:107], v[180:181]
	v_pk_fma_f32 v[102:103], v[102:103], v[182:183], v[108:109]
	v_pk_fma_f32 v[108:109], v[228:229], v[110:111], v[116:117] op_sel:[1,0,0] op_sel_hi:[1,1,0] neg_lo:[0,0,1] neg_hi:[0,0,1]
	v_pk_fma_f32 v[100:101], v[100:101], v[184:185], v[106:107]
	v_pk_fma_f32 v[106:107], v[228:229], v[114:115], v[116:117] op_sel:[1,0,0] op_sel_hi:[1,1,0] neg_lo:[0,0,1] neg_hi:[0,0,1]
	v_pk_fma_f32 v[108:109], v[164:165], v[108:109], v[172:173]
	v_pk_fma_f32 v[106:107], v[162:163], v[106:107], v[166:167]
	v_pk_fma_f32 v[96:97], v[96:97], v[170:171], v[108:109]
	v_pk_fma_f32 v[106:107], v[98:99], v[168:169], v[106:107]
	v_cvt_pk_bf16_f32 v98, v100, v101
	v_cvt_pk_bf16_f32 v100, v96, v97
	v_add_co_u32_e32 v96, vcc, s68, v120
	v_cvt_pk_bf16_f32 v99, v102, v103
	v_cvt_pk_bf16_f32 v101, v106, v107
	v_addc_co_u32_e32 v97, vcc, 0, v121, vcc
	global_store_dwordx4 v[96:97], v[98:101], off
	s_mov_b32 s42, s36
	s_nop 0
	v_add_co_u32_e32 v98, vcc, s62, v148
	s_nop 1
	v_addc_co_u32_e32 v99, vcc, 0, v149, vcc
	global_load_dwordx4 v[108:111], v[98:99], off
	global_load_dwordx2 v[118:119], v[140:141], off offset:1024
	v_add_co_u32_e32 v100, vcc, s63, v148
	s_waitcnt vmcnt(1)
	v_lshlrev_b32_e32 v200, 16, v108
	v_addc_co_u32_e32 v101, vcc, 0, v149, vcc
	global_load_dwordx4 v[114:117], v[100:101], off
	global_load_dwordx2 v[126:127], v[140:141], off offset:1152
	v_add_co_u32_e32 v102, vcc, s64, v148
	v_and_b32_e32 v201, 0xffff0000, v108
	s_nop 0
	v_addc_co_u32_e32 v103, vcc, 0, v149, vcc
	global_load_dwordx4 v[122:125], v[102:103], off
	global_load_dwordx2 v[196:197], v[140:141], off offset:1280
	v_add_co_u32_e32 v106, vcc, s65, v148
	v_lshlrev_b32_e32 v108, 16, v109
	s_nop 0
	v_addc_co_u32_e32 v107, vcc, 0, v149, vcc
	global_load_dwordx4 v[192:195], v[106:107], off
	global_load_dwordx2 v[198:199], v[140:141], off offset:1408
	v_and_b32_e32 v109, 0xffff0000, v109
	s_waitcnt vmcnt(6)
	v_pk_mul_f32 v[204:205], v[118:119], v[118:119] op_sel:[0,1] op_sel_hi:[1,0]
	v_lshlrev_b32_e32 v202, 16, v110
	v_pk_fma_f32 v[108:109], v[118:119], v[108:109], v[204:205] op_sel:[1,0,0] op_sel_hi:[1,1,0] neg_lo:[0,0,1] neg_hi:[0,0,1]
	v_and_b32_e32 v203, 0xffff0000, v110
	v_lshlrev_b32_e32 v110, 16, v111
	v_and_b32_e32 v111, 0xffff0000, v111
	v_pk_fma_f32 v[108:109], v[174:175], v[108:109], v[178:179]
	v_pk_fma_f32 v[200:201], v[118:119], v[200:201], v[204:205] op_sel:[1,0,0] op_sel_hi:[1,1,0] neg_lo:[0,0,1] neg_hi:[0,0,1]
	v_pk_fma_f32 v[94:95], v[94:95], v[182:183], v[108:109]
	v_pk_fma_f32 v[108:109], v[118:119], v[110:111], v[204:205] op_sel:[1,0,0] op_sel_hi:[1,1,0] neg_lo:[0,0,1] neg_hi:[0,0,1]
	v_pk_fma_f32 v[110:111], v[118:119], v[202:203], v[204:205] op_sel:[1,0,0] op_sel_hi:[1,1,0] neg_lo:[0,0,1] neg_hi:[0,0,1]
	v_pk_fma_f32 v[200:201], v[176:177], v[200:201], v[180:181]
	v_pk_fma_f32 v[110:111], v[164:165], v[110:111], v[172:173]
	v_pk_fma_f32 v[92:93], v[92:93], v[184:185], v[200:201]
	v_pk_fma_f32 v[108:109], v[162:163], v[108:109], v[166:167]
	v_pk_fma_f32 v[88:89], v[88:89], v[170:171], v[110:111]
	v_pk_fma_f32 v[108:109], v[90:91], v[168:169], v[108:109]
	v_cvt_pk_bf16_f32 v90, v92, v93
	v_cvt_pk_bf16_f32 v92, v88, v89
	v_add_co_u32_e32 v88, vcc, s62, v120
	v_cvt_pk_bf16_f32 v91, v94, v95
	v_cvt_pk_bf16_f32 v93, v108, v109
	v_addc_co_u32_e32 v89, vcc, 0, v121, vcc
	global_store_dwordx4 v[88:89], v[90:93], off
	s_waitcnt vmcnt(6)
	v_lshlrev_b32_e32 v94, 16, v116
	v_lshlrev_b32_e32 v92, 16, v115
	v_and_b32_e32 v93, 0xffff0000, v115
	s_waitcnt vmcnt(5)
	v_pk_mul_f32 v[110:111], v[126:127], v[126:127] op_sel:[0,1] op_sel_hi:[1,0]
	v_lshlrev_b32_e32 v90, 16, v114
	v_and_b32_e32 v91, 0xffff0000, v114
	v_pk_fma_f32 v[92:93], v[126:127], v[92:93], v[110:111] op_sel:[1,0,0] op_sel_hi:[1,1,0] neg_lo:[0,0,1] neg_hi:[0,0,1]
	v_and_b32_e32 v95, 0xffff0000, v116
	v_pk_fma_f32 v[90:91], v[126:127], v[90:91], v[110:111] op_sel:[1,0,0] op_sel_hi:[1,1,0] neg_lo:[0,0,1] neg_hi:[0,0,1]
	v_pk_fma_f32 v[92:93], v[174:175], v[92:93], v[178:179]
	v_lshlrev_b32_e32 v108, 16, v117
	v_and_b32_e32 v109, 0xffff0000, v117
	v_pk_fma_f32 v[90:91], v[176:177], v[90:91], v[180:181]
	v_pk_fma_f32 v[86:87], v[86:87], v[182:183], v[92:93]
	v_pk_fma_f32 v[92:93], v[126:127], v[94:95], v[110:111] op_sel:[1,0,0] op_sel_hi:[1,1,0] neg_lo:[0,0,1] neg_hi:[0,0,1]
	v_pk_fma_f32 v[84:85], v[84:85], v[184:185], v[90:91]
	v_pk_fma_f32 v[90:91], v[126:127], v[108:109], v[110:111] op_sel:[1,0,0] op_sel_hi:[1,1,0] neg_lo:[0,0,1] neg_hi:[0,0,1]
	v_pk_fma_f32 v[92:93], v[164:165], v[92:93], v[172:173]
	v_pk_fma_f32 v[90:91], v[162:163], v[90:91], v[166:167]
	v_pk_fma_f32 v[80:81], v[80:81], v[170:171], v[92:93]
	v_pk_fma_f32 v[90:91], v[82:83], v[168:169], v[90:91]
	v_cvt_pk_bf16_f32 v82, v84, v85
	v_cvt_pk_bf16_f32 v84, v80, v81
	v_add_co_u32_e32 v80, vcc, s63, v120
	v_cvt_pk_bf16_f32 v83, v86, v87
	v_cvt_pk_bf16_f32 v85, v90, v91
	v_addc_co_u32_e32 v81, vcc, 0, v121, vcc
	global_store_dwordx4 v[80:81], v[82:85], off
	s_waitcnt vmcnt(4)
; __device__ __forceinline__ u32x4 pack8f(f32x4 lo, f32x4 hi) { u32x4 w; w.x = cvtpk(lo[0], lo[1]); w.y = cvtpk(lo[2], lo[3]); w.z = cvtpk(hi[0], hi[1]); w.w = cvtpk(hi[2], hi[3]); return w; }
;     __device__ __forceinline__ void operator()(const Acc& acc, const Unit& u, int wr, int wc, int fr, int fq) const {
;     ...
;         for (int bj = 0; bj < 2; ++bj) {
;             f32x4 gm[2], G[2], Bc[2];
; #pragma unroll
;             for (int n = 0; n < 2; ++n) { const int c = col0 + bj * 128 + n * 4; gm[n] = *(const f32x4*)(gate + (size_t)b * NADA + c) + 1.0f; G[n] = *(const f32x4*)(lg + c) * ALPHA; Bc[n] = *(const f32x4*)(lb + c) * ALPHA; }
; #pragma unroll
;             for (int hf = 0; hf < 2; ++hf) {
;                 u32x4 yv[4]; f32x2 st[4];
; #pragma unroll
;                 for (int m = 0; m < 4; ++m) { const int row = rowb + hf * 128 + m * 16; yv[m] = *(const u32x4*)(y1 + yb + (size_t)(hf * 128 + m * 16) * 256 + bj * 128); st[m] = *(const f32x2*)(stats + (size_t)row * 2); }
; #pragma unroll
;                 for (int m = 0; m < 4; ++m) { const int row = rowb + hf * 128 + m * 16;
;                     f32x4 lo, hi; unpack8(yv[m], lo, hi); const float r = st[m][1], mr = st[m][0] * r;
;                     lo = (lo * r - mr) * G[0] + Bc[0] + gm[0] * acc[hf][bj][m][0]; hi = (hi * r - mr) * G[1] + Bc[1] + gm[1] * acc[hf][bj][m][1];
;                     *(u32x4*)(y2 + yb + (size_t)(hf * 128 + m * 16) * 256 + bj * 128) = pack8f(lo, hi); }
	v_pk_mul_f32 v[92:93], v[196:197], v[196:197] op_sel:[0,1] op_sel_hi:[1,0]
	v_lshlrev_b32_e32 v86, 16, v124
	v_lshlrev_b32_e32 v84, 16, v123
	v_and_b32_e32 v85, 0xffff0000, v123
	v_lshlrev_b32_e32 v82, 16, v122
	v_and_b32_e32 v83, 0xffff0000, v122
	v_pk_fma_f32 v[84:85], v[196:197], v[84:85], v[92:93] op_sel:[1,0,0] op_sel_hi:[1,1,0] neg_lo:[0,0,1] neg_hi:[0,0,1]
	v_and_b32_e32 v87, 0xffff0000, v124
	v_pk_fma_f32 v[82:83], v[196:197], v[82:83], v[92:93] op_sel:[1,0,0] op_sel_hi:[1,1,0] neg_lo:[0,0,1] neg_hi:[0,0,1]
	v_pk_fma_f32 v[84:85], v[174:175], v[84:85], v[178:179]
	v_lshlrev_b32_e32 v90, 16, v125
	v_and_b32_e32 v91, 0xffff0000, v125
	v_pk_fma_f32 v[82:83], v[176:177], v[82:83], v[180:181]
	v_pk_fma_f32 v[78:79], v[78:79], v[182:183], v[84:85]
	v_pk_fma_f32 v[84:85], v[196:197], v[86:87], v[92:93] op_sel:[1,0,0] op_sel_hi:[1,1,0] neg_lo:[0,0,1] neg_hi:[0,0,1]
	v_pk_fma_f32 v[76:77], v[76:77], v[184:185], v[82:83]
	v_pk_fma_f32 v[82:83], v[196:197], v[90:91], v[92:93] op_sel:[1,0,0] op_sel_hi:[1,1,0] neg_lo:[0,0,1] neg_hi:[0,0,1]
	v_pk_fma_f32 v[84:85], v[164:165], v[84:85], v[172:173]
	v_pk_fma_f32 v[82:83], v[162:163], v[82:83], v[166:167]
	v_pk_fma_f32 v[72:73], v[72:73], v[170:171], v[84:85]
	v_pk_fma_f32 v[82:83], v[74:75], v[168:169], v[82:83]
	v_cvt_pk_bf16_f32 v74, v76, v77
	v_cvt_pk_bf16_f32 v76, v72, v73
	v_add_co_u32_e32 v72, vcc, s64, v120
	v_cvt_pk_bf16_f32 v75, v78, v79
	v_cvt_pk_bf16_f32 v77, v82, v83
	v_addc_co_u32_e32 v73, vcc, 0, v121, vcc
	global_store_dwordx4 v[72:73], v[74:77], off
	s_waitcnt vmcnt(3)
	v_pk_mul_f32 v[84:85], v[198:199], v[198:199] op_sel:[0,1] op_sel_hi:[1,0]
	v_lshlrev_b32_e32 v78, 16, v194
	v_lshlrev_b32_e32 v76, 16, v193
	v_and_b32_e32 v77, 0xffff0000, v193
	v_lshlrev_b32_e32 v74, 16, v192
	v_and_b32_e32 v75, 0xffff0000, v192
	v_pk_fma_f32 v[76:77], v[198:199], v[76:77], v[84:85] op_sel:[1,0,0] op_sel_hi:[1,1,0] neg_lo:[0,0,1] neg_hi:[0,0,1]
	v_and_b32_e32 v79, 0xffff0000, v194
	v_pk_fma_f32 v[74:75], v[198:199], v[74:75], v[84:85] op_sel:[1,0,0] op_sel_hi:[1,1,0] neg_lo:[0,0,1] neg_hi:[0,0,1]
	v_pk_fma_f32 v[76:77], v[174:175], v[76:77], v[178:179]
	v_lshlrev_b32_e32 v82, 16, v195
	v_and_b32_e32 v83, 0xffff0000, v195
	v_pk_fma_f32 v[74:75], v[176:177], v[74:75], v[180:181]
	v_pk_fma_f32 v[70:71], v[70:71], v[182:183], v[76:77]
	v_pk_fma_f32 v[76:77], v[198:199], v[78:79], v[84:85] op_sel:[1,0,0] op_sel_hi:[1,1,0] neg_lo:[0,0,1] neg_hi:[0,0,1]
	v_pk_fma_f32 v[68:69], v[68:69], v[184:185], v[74:75]
	v_pk_fma_f32 v[74:75], v[198:199], v[82:83], v[84:85] op_sel:[1,0,0] op_sel_hi:[1,1,0] neg_lo:[0,0,1] neg_hi:[0,0,1]
	v_pk_fma_f32 v[76:77], v[164:165], v[76:77], v[172:173]
	v_pk_fma_f32 v[74:75], v[162:163], v[74:75], v[166:167]
	v_pk_fma_f32 v[64:65], v[64:65], v[170:171], v[76:77]
	v_pk_fma_f32 v[74:75], v[66:67], v[168:169], v[74:75]
	v_cvt_pk_bf16_f32 v66, v68, v69
	v_cvt_pk_bf16_f32 v68, v64, v65
	v_add_co_u32_e32 v64, vcc, s65, v120
	v_cvt_pk_bf16_f32 v67, v70, v71
	v_cvt_pk_bf16_f32 v69, v74, v75
	v_addc_co_u32_e32 v65, vcc, 0, v121, vcc
	global_store_dwordx4 v[64:65], v[66:69], off
	global_load_dwordx4 v[66:69], v[146:147], off offset:512
	global_load_dwordx4 v[82:85], v[142:143], off offset:512
	global_load_dwordx4 v[108:111], v[144:145], off offset:512
	global_load_dwordx4 v[114:117], v[146:147], off offset:528
	global_load_dwordx4 v[122:125], v[142:143], off offset:528
	s_nop 0
	global_load_dwordx4 v[142:145], v[144:145], off offset:528
	s_nop 0
	global_load_dwordx4 v[146:149], v[148:149], off offset:256
	s_nop 0
	global_load_dwordx2 v[118:119], v[140:141], off
	global_load_dwordx4 v[162:165], v[150:151], off offset:256
	global_load_dwordx2 v[126:127], v[152:153], off
	s_nop 0
	global_load_dwordx4 v[150:153], v[158:159], off offset:256
	s_nop 0
	global_load_dwordx2 v[158:159], v[160:161], off
	s_and_b64 vcc, exec, s[2:3]
	s_waitcnt vmcnt(11)
	v_pk_add_f32 v[74:75], v[68:69], 1.0 op_sel_hi:[1,0]
	v_pk_add_f32 v[76:77], v[66:67], 1.0 op_sel_hi:[1,0]
	s_waitcnt vmcnt(9)
	v_pk_mul_f32 v[92:93], v[110:111], s[28:29] op_sel_hi:[1,0]
	v_pk_mul_f32 v[94:95], v[108:109], s[28:29] op_sel_hi:[1,0]
	s_waitcnt vmcnt(8)
	v_pk_add_f32 v[68:69], v[114:115], 1.0 op_sel_hi:[1,0]
	global_load_dwordx4 v[108:111], v[156:157], off offset:256
	global_load_dwordx2 v[114:115], v[154:155], off
	v_pk_mul_f32 v[90:91], v[82:83], s[28:29] op_sel_hi:[1,0]
	v_pk_add_f32 v[66:67], v[116:117], 1.0 op_sel_hi:[1,0]
	s_waitcnt vmcnt(8)
	v_pk_mul_f32 v[82:83], v[144:145], s[28:29] op_sel_hi:[1,0]
	s_waitcnt vmcnt(7)
	v_lshlrev_b32_e32 v116, 16, v146
	v_and_b32_e32 v117, 0xffff0000, v146
	s_waitcnt vmcnt(6)
	v_pk_mul_f32 v[144:145], v[118:119], v[118:119] op_sel:[0,1] op_sel_hi:[1,0]
	v_pk_mul_f32 v[86:87], v[84:85], s[28:29] op_sel_hi:[1,0]
	v_pk_fma_f32 v[116:117], v[118:119], v[116:117], v[144:145] op_sel:[1,0,0] op_sel_hi:[1,1,0] neg_lo:[0,0,1] neg_hi:[0,0,1]
	v_pk_mul_f32 v[70:71], v[124:125], s[28:29] op_sel_hi:[1,0]
	v_pk_mul_f32 v[78:79], v[122:123], s[28:29] op_sel_hi:[1,0]
	v_pk_mul_f32 v[84:85], v[142:143], s[28:29] op_sel_hi:[1,0]
	v_lshlrev_b32_e32 v122, 16, v147
	v_and_b32_e32 v123, 0xffff0000, v147
	v_lshlrev_b32_e32 v124, 16, v148
	v_and_b32_e32 v125, 0xffff0000, v148
	v_lshlrev_b32_e32 v142, 16, v149
	v_and_b32_e32 v143, 0xffff0000, v149
	v_pk_fma_f32 v[116:117], v[90:91], v[116:117], v[94:95]
	v_pk_fma_f32 v[122:123], v[118:119], v[122:123], v[144:145] op_sel:[1,0,0] op_sel_hi:[1,1,0] neg_lo:[0,0,1] neg_hi:[0,0,1]
	v_pk_fma_f32 v[60:61], v[60:61], v[76:77], v[116:117]
	v_pk_fma_f32 v[116:117], v[118:119], v[124:125], v[144:145] op_sel:[1,0,0] op_sel_hi:[1,1,0] neg_lo:[0,0,1] neg_hi:[0,0,1]
	v_pk_fma_f32 v[118:119], v[118:119], v[142:143], v[144:145] op_sel:[1,0,0] op_sel_hi:[1,1,0] neg_lo:[0,0,1] neg_hi:[0,0,1]
	v_pk_fma_f32 v[122:123], v[86:87], v[122:123], v[92:93]
	v_pk_fma_f32 v[118:119], v[70:71], v[118:119], v[82:83]
	v_pk_fma_f32 v[116:117], v[78:79], v[116:117], v[84:85]
	v_pk_fma_f32 v[62:63], v[62:63], v[74:75], v[122:123]
	v_pk_fma_f32 v[118:119], v[58:59], v[66:67], v[118:119]
	v_pk_fma_f32 v[58:59], v[56:57], v[68:69], v[116:117]
	v_cvt_pk_bf16_f32 v56, v60, v61
	v_cvt_pk_bf16_f32 v57, v62, v63
	v_cvt_pk_bf16_f32 v58, v58, v59
	v_cvt_pk_bf16_f32 v59, v118, v119
	global_store_dwordx4 v[120:121], v[56:59], off offset:256
	s_waitcnt vmcnt(5)
; __device__ __forceinline__ u32x4 pack8f(f32x4 lo, f32x4 hi) { u32x4 w; w.x = cvtpk(lo[0], lo[1]); w.y = cvtpk(lo[2], lo[3]); w.z = cvtpk(hi[0], hi[1]); w.w = cvtpk(hi[2], hi[3]); return w; }
;     __device__ __forceinline__ void operator()(const Acc& acc, const Unit& u, int wr, int wc, int fr, int fq) const {
;     ...
;             for (int hf = 0; hf < 2; ++hf) {
;                 u32x4 yv[4]; f32x2 st[4];
; #pragma unroll
;                 for (int m = 0; m < 4; ++m) { const int row = rowb + hf * 128 + m * 16; yv[m] = *(const u32x4*)(y1 + yb + (size_t)(hf * 128 + m * 16) * 256 + bj * 128); st[m] = *(const f32x2*)(stats + (size_t)row * 2); }
; #pragma unroll
;                 for (int m = 0; m < 4; ++m) { const int row = rowb + hf * 128 + m * 16;
;                     f32x4 lo, hi; unpack8(yv[m], lo, hi); const float r = st[m][1], mr = st[m][0] * r;
;                     lo = (lo * r - mr) * G[0] + Bc[0] + gm[0] * acc[hf][bj][m][0]; hi = (hi * r - mr) * G[1] + Bc[1] + gm[1] * acc[hf][bj][m][1];
;                     *(u32x4*)(y2 + yb + (size_t)(hf * 128 + m * 16) * 256 + bj * 128) = pack8f(lo, hi); }
	v_pk_mul_f32 v[116:117], v[126:127], v[126:127] op_sel:[0,1] op_sel_hi:[1,0]
	v_lshlrev_b32_e32 v60, 16, v164
	v_lshlrev_b32_e32 v56, 16, v162
	v_and_b32_e32 v57, 0xffff0000, v162
	v_lshlrev_b32_e32 v58, 16, v163
	v_and_b32_e32 v59, 0xffff0000, v163
	v_pk_fma_f32 v[58:59], v[126:127], v[58:59], v[116:117] op_sel:[1,0,0] op_sel_hi:[1,1,0] neg_lo:[0,0,1] neg_hi:[0,0,1]
	v_pk_fma_f32 v[56:57], v[126:127], v[56:57], v[116:117] op_sel:[1,0,0] op_sel_hi:[1,1,0] neg_lo:[0,0,1] neg_hi:[0,0,1]
	v_and_b32_e32 v61, 0xffff0000, v164
	v_lshlrev_b32_e32 v62, 16, v165
	v_and_b32_e32 v63, 0xffff0000, v165
	v_pk_fma_f32 v[56:57], v[90:91], v[56:57], v[94:95]
	v_pk_fma_f32 v[58:59], v[86:87], v[58:59], v[92:93]
	v_pk_fma_f32 v[52:53], v[52:53], v[76:77], v[56:57]
	v_pk_fma_f32 v[54:55], v[54:55], v[74:75], v[58:59]
	v_pk_fma_f32 v[56:57], v[126:127], v[62:63], v[116:117] op_sel:[1,0,0] op_sel_hi:[1,1,0] neg_lo:[0,0,1] neg_hi:[0,0,1]
	v_pk_fma_f32 v[58:59], v[126:127], v[60:61], v[116:117] op_sel:[1,0,0] op_sel_hi:[1,1,0] neg_lo:[0,0,1] neg_hi:[0,0,1]
	v_pk_fma_f32 v[56:57], v[70:71], v[56:57], v[82:83]
	v_pk_fma_f32 v[58:59], v[78:79], v[58:59], v[84:85]
	v_pk_fma_f32 v[56:57], v[50:51], v[66:67], v[56:57]
	v_pk_fma_f32 v[50:51], v[48:49], v[68:69], v[58:59]
	v_cvt_pk_bf16_f32 v48, v52, v53
	v_cvt_pk_bf16_f32 v49, v54, v55
	v_cvt_pk_bf16_f32 v50, v50, v51
	v_cvt_pk_bf16_f32 v51, v56, v57
	global_store_dwordx4 v[112:113], v[48:51], off offset:256
	s_waitcnt vmcnt(4)
	v_pk_mul_f32 v[56:57], v[158:159], v[158:159] op_sel:[0,1] op_sel_hi:[1,0]
	v_lshlrev_b32_e32 v52, 16, v152
	v_lshlrev_b32_e32 v48, 16, v150
	v_and_b32_e32 v49, 0xffff0000, v150
	v_lshlrev_b32_e32 v50, 16, v151
	v_and_b32_e32 v51, 0xffff0000, v151
	v_pk_fma_f32 v[50:51], v[158:159], v[50:51], v[56:57] op_sel:[1,0,0] op_sel_hi:[1,1,0] neg_lo:[0,0,1] neg_hi:[0,0,1]
	v_pk_fma_f32 v[48:49], v[158:159], v[48:49], v[56:57] op_sel:[1,0,0] op_sel_hi:[1,1,0] neg_lo:[0,0,1] neg_hi:[0,0,1]
	v_and_b32_e32 v53, 0xffff0000, v152
	v_lshlrev_b32_e32 v54, 16, v153
	v_and_b32_e32 v55, 0xffff0000, v153
	v_pk_fma_f32 v[48:49], v[90:91], v[48:49], v[94:95]
	v_pk_fma_f32 v[50:51], v[86:87], v[50:51], v[92:93]
	v_pk_fma_f32 v[44:45], v[44:45], v[76:77], v[48:49]
	v_pk_fma_f32 v[46:47], v[46:47], v[74:75], v[50:51]
	v_pk_fma_f32 v[48:49], v[158:159], v[54:55], v[56:57] op_sel:[1,0,0] op_sel_hi:[1,1,0] neg_lo:[0,0,1] neg_hi:[0,0,1]
	v_pk_fma_f32 v[50:51], v[158:159], v[52:53], v[56:57] op_sel:[1,0,0] op_sel_hi:[1,1,0] neg_lo:[0,0,1] neg_hi:[0,0,1]
	v_pk_fma_f32 v[48:49], v[70:71], v[48:49], v[82:83]
	v_pk_fma_f32 v[50:51], v[78:79], v[50:51], v[84:85]
	v_pk_fma_f32 v[48:49], v[42:43], v[66:67], v[48:49]
	v_pk_fma_f32 v[42:43], v[40:41], v[68:69], v[50:51]
	v_cvt_pk_bf16_f32 v40, v44, v45
	v_cvt_pk_bf16_f32 v41, v46, v47
	v_cvt_pk_bf16_f32 v42, v42, v43
	v_cvt_pk_bf16_f32 v43, v48, v49
	global_store_dwordx4 v[104:105], v[40:43], off offset:256
	s_waitcnt vmcnt(3)
	v_pk_mul_f32 v[48:49], v[114:115], v[114:115] op_sel:[0,1] op_sel_hi:[1,0]
	v_lshlrev_b32_e32 v44, 16, v110
	v_lshlrev_b32_e32 v40, 16, v108
	v_and_b32_e32 v41, 0xffff0000, v108
	v_lshlrev_b32_e32 v42, 16, v109
	v_and_b32_e32 v43, 0xffff0000, v109
	v_pk_fma_f32 v[42:43], v[114:115], v[42:43], v[48:49] op_sel:[1,0,0] op_sel_hi:[1,1,0] neg_lo:[0,0,1] neg_hi:[0,0,1]
	v_pk_fma_f32 v[40:41], v[114:115], v[40:41], v[48:49] op_sel:[1,0,0] op_sel_hi:[1,1,0] neg_lo:[0,0,1] neg_hi:[0,0,1]
	v_and_b32_e32 v45, 0xffff0000, v110
	v_lshlrev_b32_e32 v46, 16, v111
	v_and_b32_e32 v47, 0xffff0000, v111
	v_pk_fma_f32 v[40:41], v[90:91], v[40:41], v[94:95]
	v_pk_fma_f32 v[42:43], v[86:87], v[42:43], v[92:93]
	v_pk_fma_f32 v[36:37], v[36:37], v[76:77], v[40:41]
	v_pk_fma_f32 v[38:39], v[38:39], v[74:75], v[42:43]
	v_pk_fma_f32 v[40:41], v[114:115], v[46:47], v[48:49] op_sel:[1,0,0] op_sel_hi:[1,1,0] neg_lo:[0,0,1] neg_hi:[0,0,1]
	v_pk_fma_f32 v[42:43], v[114:115], v[44:45], v[48:49] op_sel:[1,0,0] op_sel_hi:[1,1,0] neg_lo:[0,0,1] neg_hi:[0,0,1]
	v_pk_fma_f32 v[40:41], v[70:71], v[40:41], v[82:83]
	v_pk_fma_f32 v[42:43], v[78:79], v[42:43], v[84:85]
	v_pk_fma_f32 v[40:41], v[34:35], v[66:67], v[40:41]
	v_pk_fma_f32 v[34:35], v[32:33], v[68:69], v[42:43]
	v_cvt_pk_bf16_f32 v32, v36, v37
	v_cvt_pk_bf16_f32 v33, v38, v39
	v_cvt_pk_bf16_f32 v34, v34, v35
	v_cvt_pk_bf16_f32 v35, v40, v41
	global_store_dwordx4 v[96:97], v[32:35], off offset:256
	global_load_dwordx4 v[32:35], v[98:99], off offset:256
	global_load_dwordx2 v[48:49], v[140:141], off offset:1024
	global_load_dwordx4 v[36:39], v[100:101], off offset:256
	global_load_dwordx2 v[50:51], v[140:141], off offset:1152
	global_load_dwordx4 v[40:43], v[102:103], off offset:256
	global_load_dwordx2 v[52:53], v[140:141], off offset:1280
	global_load_dwordx4 v[44:47], v[106:107], off offset:256
	global_load_dwordx2 v[54:55], v[140:141], off offset:1408
	s_waitcnt vmcnt(7)
	v_lshlrev_b32_e32 v56, 16, v32
	v_and_b32_e32 v57, 0xffff0000, v32
	v_lshlrev_b32_e32 v32, 16, v33
	v_and_b32_e32 v33, 0xffff0000, v33
	s_waitcnt vmcnt(6)
; #define PG8_WAIT_V(n) asm volatile("s_waitcnt vmcnt(" #n ")" ::: "memory")
; #define PG8_BAR __builtin_amdgcn_s_barrier()
; __device__ __forceinline__ u32x4 pack8f(f32x4 lo, f32x4 hi) { u32x4 w; w.x = cvtpk(lo[0], lo[1]); w.y = cvtpk(lo[2], lo[3]); w.z = cvtpk(hi[0], hi[1]); w.w = cvtpk(hi[2], hi[3]); return w; }
;     ...
;         if (!has_next) break;
; #pragma unroll
;         for (int a = 0; a < 2; ++a)
; #pragma unroll
;             for (int b = 0; b < 2; ++b)
; #pragma unroll
;                 for (int m = 0; m < 4; ++m)
; #pragma unroll
;                     for (int n = 0; n < 2; ++n) acc[a][b][m][n] = (f32x4){0.f, 0.f, 0.f, 0.f};
;         cur = nxt; cA = nA; cB = nB; ++ui;
;         if constexpr (ALIGN) { if (wr == 1) PG8_BAR; }
;     }
;     PG8_WAIT_V(0);
;     if constexpr (!ALIGN) { if (wr == 0) PG8_BAR; }
;     PG8_BAR;
;     __device__ __forceinline__ void operator()(const Acc& acc, const Unit& u, int wr, int wc, int fr, int fq) const {
;     ...
;             for (int hf = 0; hf < 2; ++hf) {
;                 u32x4 yv[4]; f32x2 st[4];
; #pragma unroll
;                 for (int m = 0; m < 4; ++m) { const int row = rowb + hf * 128 + m * 16; yv[m] = *(const u32x4*)(y1 + yb + (size_t)(hf * 128 + m * 16) * 256 + bj * 128); st[m] = *(const f32x2*)(stats + (size_t)row * 2); }
; #pragma unroll
;                 for (int m = 0; m < 4; ++m) { const int row = rowb + hf * 128 + m * 16;
;                     f32x4 lo, hi; unpack8(yv[m], lo, hi); const float r = st[m][1], mr = st[m][0] * r;
;                     lo = (lo * r - mr) * G[0] + Bc[0] + gm[0] * acc[hf][bj][m][0]; hi = (hi * r - mr) * G[1] + Bc[1] + gm[1] * acc[hf][bj][m][1];
;                     *(u32x4*)(y2 + yb + (size_t)(hf * 128 + m * 16) * 256 + bj * 128) = pack8f(lo, hi); }
;                 asm volatile("" ::: "memory");
;             }
;             asm volatile("" ::: "memory");
;         }
	v_pk_mul_f32 v[60:61], v[48:49], v[48:49] op_sel:[0,1] op_sel_hi:[1,0]
	v_lshlrev_b32_e32 v58, 16, v34
	v_pk_fma_f32 v[32:33], v[48:49], v[32:33], v[60:61] op_sel:[1,0,0] op_sel_hi:[1,1,0] neg_lo:[0,0,1] neg_hi:[0,0,1]
	v_and_b32_e32 v59, 0xffff0000, v34
	v_lshlrev_b32_e32 v34, 16, v35
	v_and_b32_e32 v35, 0xffff0000, v35
	v_pk_fma_f32 v[32:33], v[86:87], v[32:33], v[92:93]
	v_pk_fma_f32 v[56:57], v[48:49], v[56:57], v[60:61] op_sel:[1,0,0] op_sel_hi:[1,1,0] neg_lo:[0,0,1] neg_hi:[0,0,1]
	v_pk_fma_f32 v[30:31], v[30:31], v[74:75], v[32:33]
	v_pk_fma_f32 v[32:33], v[48:49], v[34:35], v[60:61] op_sel:[1,0,0] op_sel_hi:[1,1,0] neg_lo:[0,0,1] neg_hi:[0,0,1]
	v_pk_fma_f32 v[34:35], v[48:49], v[58:59], v[60:61] op_sel:[1,0,0] op_sel_hi:[1,1,0] neg_lo:[0,0,1] neg_hi:[0,0,1]
	v_pk_fma_f32 v[56:57], v[90:91], v[56:57], v[94:95]
	v_pk_fma_f32 v[34:35], v[78:79], v[34:35], v[84:85]
	v_pk_fma_f32 v[32:33], v[70:71], v[32:33], v[82:83]
	v_pk_fma_f32 v[28:29], v[28:29], v[76:77], v[56:57]
	v_pk_fma_f32 v[32:33], v[26:27], v[66:67], v[32:33]
	v_pk_fma_f32 v[26:27], v[24:25], v[68:69], v[34:35]
	v_cvt_pk_bf16_f32 v24, v28, v29
	v_cvt_pk_bf16_f32 v25, v30, v31
	v_cvt_pk_bf16_f32 v26, v26, v27
	v_cvt_pk_bf16_f32 v27, v32, v33
	global_store_dwordx4 v[88:89], v[24:27], off offset:256
	s_waitcnt vmcnt(5)
	v_pk_mul_f32 v[32:33], v[50:51], v[50:51] op_sel:[0,1] op_sel_hi:[1,0]
	v_lshlrev_b32_e32 v28, 16, v38
	v_lshlrev_b32_e32 v24, 16, v36
	v_and_b32_e32 v25, 0xffff0000, v36
	v_lshlrev_b32_e32 v26, 16, v37
	v_and_b32_e32 v27, 0xffff0000, v37
	v_pk_fma_f32 v[26:27], v[50:51], v[26:27], v[32:33] op_sel:[1,0,0] op_sel_hi:[1,1,0] neg_lo:[0,0,1] neg_hi:[0,0,1]
	v_pk_fma_f32 v[24:25], v[50:51], v[24:25], v[32:33] op_sel:[1,0,0] op_sel_hi:[1,1,0] neg_lo:[0,0,1] neg_hi:[0,0,1]
	v_and_b32_e32 v29, 0xffff0000, v38
	v_lshlrev_b32_e32 v30, 16, v39
	v_and_b32_e32 v31, 0xffff0000, v39
	v_pk_fma_f32 v[24:25], v[90:91], v[24:25], v[94:95]
	v_pk_fma_f32 v[26:27], v[86:87], v[26:27], v[92:93]
	v_pk_fma_f32 v[20:21], v[20:21], v[76:77], v[24:25]
	v_pk_fma_f32 v[22:23], v[22:23], v[74:75], v[26:27]
	v_pk_fma_f32 v[24:25], v[50:51], v[30:31], v[32:33] op_sel:[1,0,0] op_sel_hi:[1,1,0] neg_lo:[0,0,1] neg_hi:[0,0,1]
	v_pk_fma_f32 v[26:27], v[50:51], v[28:29], v[32:33] op_sel:[1,0,0] op_sel_hi:[1,1,0] neg_lo:[0,0,1] neg_hi:[0,0,1]
	v_pk_fma_f32 v[24:25], v[70:71], v[24:25], v[82:83]
	v_pk_fma_f32 v[26:27], v[78:79], v[26:27], v[84:85]
	v_pk_fma_f32 v[24:25], v[18:19], v[66:67], v[24:25]
	v_pk_fma_f32 v[18:19], v[16:17], v[68:69], v[26:27]
	v_cvt_pk_bf16_f32 v16, v20, v21
	v_cvt_pk_bf16_f32 v17, v22, v23
	v_cvt_pk_bf16_f32 v18, v18, v19
	v_cvt_pk_bf16_f32 v19, v24, v25
	global_store_dwordx4 v[80:81], v[16:19], off offset:256
	s_waitcnt vmcnt(4)
	v_pk_mul_f32 v[24:25], v[52:53], v[52:53] op_sel:[0,1] op_sel_hi:[1,0]
	v_lshlrev_b32_e32 v20, 16, v42
	v_lshlrev_b32_e32 v16, 16, v40
	v_and_b32_e32 v17, 0xffff0000, v40
	v_lshlrev_b32_e32 v18, 16, v41
	v_and_b32_e32 v19, 0xffff0000, v41
	v_pk_fma_f32 v[18:19], v[52:53], v[18:19], v[24:25] op_sel:[1,0,0] op_sel_hi:[1,1,0] neg_lo:[0,0,1] neg_hi:[0,0,1]
	v_pk_fma_f32 v[16:17], v[52:53], v[16:17], v[24:25] op_sel:[1,0,0] op_sel_hi:[1,1,0] neg_lo:[0,0,1] neg_hi:[0,0,1]
	v_and_b32_e32 v21, 0xffff0000, v42
	v_lshlrev_b32_e32 v22, 16, v43
	v_and_b32_e32 v23, 0xffff0000, v43
	v_pk_fma_f32 v[16:17], v[90:91], v[16:17], v[94:95]
	v_pk_fma_f32 v[18:19], v[86:87], v[18:19], v[92:93]
	v_pk_fma_f32 v[12:13], v[12:13], v[76:77], v[16:17]
	v_pk_fma_f32 v[14:15], v[14:15], v[74:75], v[18:19]
	v_pk_fma_f32 v[16:17], v[52:53], v[22:23], v[24:25] op_sel:[1,0,0] op_sel_hi:[1,1,0] neg_lo:[0,0,1] neg_hi:[0,0,1]
	v_pk_fma_f32 v[18:19], v[52:53], v[20:21], v[24:25] op_sel:[1,0,0] op_sel_hi:[1,1,0] neg_lo:[0,0,1] neg_hi:[0,0,1]
	v_pk_fma_f32 v[16:17], v[70:71], v[16:17], v[82:83]
	v_pk_fma_f32 v[18:19], v[78:79], v[18:19], v[84:85]
	v_pk_fma_f32 v[16:17], v[10:11], v[66:67], v[16:17]
	v_pk_fma_f32 v[10:11], v[8:9], v[68:69], v[18:19]
	v_cvt_pk_bf16_f32 v8, v12, v13
	v_cvt_pk_bf16_f32 v9, v14, v15
	v_cvt_pk_bf16_f32 v10, v10, v11
	v_cvt_pk_bf16_f32 v11, v16, v17
	global_store_dwordx4 v[72:73], v[8:11], off offset:256
	s_waitcnt vmcnt(3)
	v_pk_mul_f32 v[16:17], v[54:55], v[54:55] op_sel:[0,1] op_sel_hi:[1,0]
	v_lshlrev_b32_e32 v12, 16, v46
	v_lshlrev_b32_e32 v8, 16, v44
	v_and_b32_e32 v9, 0xffff0000, v44
	v_lshlrev_b32_e32 v10, 16, v45
	v_and_b32_e32 v11, 0xffff0000, v45
	v_pk_fma_f32 v[10:11], v[54:55], v[10:11], v[16:17] op_sel:[1,0,0] op_sel_hi:[1,1,0] neg_lo:[0,0,1] neg_hi:[0,0,1]
	v_pk_fma_f32 v[8:9], v[54:55], v[8:9], v[16:17] op_sel:[1,0,0] op_sel_hi:[1,1,0] neg_lo:[0,0,1] neg_hi:[0,0,1]
	v_and_b32_e32 v13, 0xffff0000, v46
	v_lshlrev_b32_e32 v14, 16, v47
	v_and_b32_e32 v15, 0xffff0000, v47
	v_pk_fma_f32 v[8:9], v[90:91], v[8:9], v[94:95]
	v_pk_fma_f32 v[10:11], v[86:87], v[10:11], v[92:93]
	v_pk_fma_f32 v[4:5], v[4:5], v[76:77], v[8:9]
	v_pk_fma_f32 v[6:7], v[6:7], v[74:75], v[10:11]
	v_pk_fma_f32 v[8:9], v[54:55], v[14:15], v[16:17] op_sel:[1,0,0] op_sel_hi:[1,1,0] neg_lo:[0,0,1] neg_hi:[0,0,1]
	v_pk_fma_f32 v[10:11], v[54:55], v[12:13], v[16:17] op_sel:[1,0,0] op_sel_hi:[1,1,0] neg_lo:[0,0,1] neg_hi:[0,0,1]
	v_pk_fma_f32 v[8:9], v[70:71], v[8:9], v[82:83]
	v_pk_fma_f32 v[10:11], v[78:79], v[10:11], v[84:85]
	v_pk_fma_f32 v[8:9], v[2:3], v[66:67], v[8:9]
	v_pk_fma_f32 v[2:3], v[0:1], v[68:69], v[10:11]
	v_cvt_pk_bf16_f32 v0, v4, v5
	v_cvt_pk_bf16_f32 v1, v6, v7
	v_cvt_pk_bf16_f32 v2, v2, v3
	v_cvt_pk_bf16_f32 v3, v8, v9
	global_store_dwordx4 v[64:65], v[0:3], off offset:256
	s_cbranch_vccz .LBB0_1274
	s_waitcnt vmcnt(0)
	s_cmpk_gt_u32 s29, 0xff
	s_cbranch_scc1 .LBB0_1285
	s_barrier
